# prologue: silu(c) staging loads all in flight; adaLN GEMV K-loop software-pipelined (double-buffered weight loads)
# speedup vs baseline: 1.1077x; 1.0034x over previous
; #define LAS __attribute__((address_space(3)))
; __device__ __forceinline__ unsigned xb_add(unsigned* p, unsigned v) { return __hip_atomic_fetch_add(p, v, __ATOMIC_RELAXED, __HIP_MEMORY_SCOPE_AGENT); }
; __device__ __forceinline__ unsigned xb_xcc_id() { return (unsigned)__builtin_amdgcn_s_getreg((3 << 11) | 20) & 0xFu; }
; __device__ __forceinline__ XcdBarrier xcd_barrier_post(unsigned* bar, volatile LAS unsigned* st) {
;     XcdBarrier b; b.bar = bar; b.x = xb_xcc_id(); b.st = st;
;     if (threadIdx.x == 0) (void)xb_add(&bar[XB_XCNT(b.x)], 1u);
;     return b;
; __global__ void __launch_bounds__(NTHREADS) mega_fwd(P p) {
;     ...
;     volatile LAS unsigned* MISC = (volatile LAS unsigned*)(LDSL + LDS_MISC);
;     if (threadIdx.x < 16) MISC[threadIdx.x] = 0u;
;     __syncthreads();
;     XcdBarrier bar = xcd_barrier_post((unsigned*)p.ws, MISC);
_Z8mega_fwd1P:
	s_mov_b32 s101, 0
	s_mov_b64 s[92:93], s[0:1]
	s_load_dwordx4 s[36:39], s[0:1], 0xa8
	s_nop 0
	s_load_dword s1, s[0:1], 0xb8
	s_mov_b32 s90, s2
	s_add_u32 s2, s92, 0xb0
	v_and_b32_e32 v184, 0x3ff, v0
	s_addc_u32 s3, s93, 0
	v_cmp_gt_u32_e32 vcc, 16, v184
	s_and_saveexec_b64 s[4:5], vcc
	v_lshl_add_u32 v1, v184, 2, 0
	v_add_u32_e32 v1, 0x26000, v1
	v_mov_b32_e32 v2, 0
	ds_write_b32 v1, v2
	s_or_b64 exec, exec, s[4:5]
	s_waitcnt lgkmcnt(0)
	s_barrier
	s_getreg_b32 s0, hwreg(HW_REG_XCC_ID, 0, 4)
	s_and_b32 s0, s0, 15
	s_mov_b32 s12, 0
	v_cmp_ne_u32_e64 s[6:7], 0, v184
	v_cmp_eq_u32_e64 s[8:9], 0, v184
	s_mov_b64 s[4:5], exec
	s_nop 0
	v_writelane_b32 v253, s8, 0
	s_nop 1
	v_writelane_b32 v253, s9, 1
	s_and_b64 s[8:9], s[4:5], s[8:9]
	s_mov_b64 exec, s[8:9]
	s_cbranch_execz .LBB0_5
	s_mov_b64 s[8:9], exec
	v_mbcnt_lo_u32_b32 v1, s8, 0
	v_mbcnt_hi_u32_b32 v1, s9, v1
	v_cmp_eq_u32_e32 vcc, 0, v1
	s_and_b64 s[10:11], exec, vcc
	s_mov_b64 exec, s[10:11]
	s_cbranch_execz .LBB0_5
	s_lshl_b32 s10, s0, 8
	s_bcnt1_i32_b64 s8, s[8:9]
	v_mov_b32_e32 v1, s10
	v_mov_b32_e32 v2, s8
	global_atomic_add v1, v2, s[36:37] offset:1024

; __device__ __forceinline__ float siluf(float v) { return v * __builtin_amdgcn_rcpf(1.f + __expf(-v)); }
; __device__ __forceinline__ void ph_prologue(const P& p, unsigned char* lds, int tid, int wave, int lane, int G) {
;     ...
;     for (int task = blockIdx.x; task < 256; task += G) {
;         if (!have) {
;             for (int i = tid; i < 9 * 1024; i += NTHREADS) { const float v = i < 8192 ? p.c[i] : p.c_ctx[i - 8192]; sv[i] = siluf(v); }
;             have = true; __syncthreads();
.LBB0_15:
	s_and_b64 vcc, exec, s[24:25]
	s_cbranch_vccnz .LBB0_20
	s_and_saveexec_b64 s[24:25], s[10:11]
	s_cbranch_execz .LBB0_19
	v_mov_b64_e32 v[8:9], v[2:3]
	global_load_dword v40, v[8:9], off
	v_lshl_add_u64 v[8:9], v[8:9], 0, s[20:21]
	global_load_dword v41, v[8:9], off
	v_lshl_add_u64 v[8:9], v[8:9], 0, s[20:21]
	global_load_dword v42, v[8:9], off
	v_lshl_add_u64 v[8:9], v[8:9], 0, s[20:21]
	global_load_dword v43, v[8:9], off
	v_lshl_add_u64 v[8:9], v[8:9], 0, s[20:21]
	global_load_dword v44, v[8:9], off
	v_lshl_add_u64 v[8:9], v[8:9], 0, s[20:21]
	global_load_dword v45, v[8:9], off
	v_lshl_add_u64 v[8:9], v[8:9], 0, s[20:21]
	global_load_dword v46, v[8:9], off
	v_lshl_add_u64 v[8:9], v[8:9], 0, s[20:21]
	global_load_dword v47, v[8:9], off
	v_lshl_add_u64 v[8:9], v[8:9], 0, s[20:21]
	global_load_dword v48, v[8:9], off
	v_lshl_add_u64 v[8:9], v[8:9], 0, s[20:21]
	global_load_dword v49, v[8:9], off
	v_lshl_add_u64 v[8:9], v[8:9], 0, s[20:21]
	global_load_dword v50, v[8:9], off
	v_lshl_add_u64 v[8:9], v[8:9], 0, s[20:21]
	global_load_dword v51, v[8:9], off
	v_lshl_add_u64 v[8:9], v[8:9], 0, s[20:21]
	global_load_dword v52, v[8:9], off
	v_lshl_add_u64 v[8:9], v[8:9], 0, s[20:21]
	global_load_dword v53, v[8:9], off
	v_lshl_add_u64 v[8:9], v[8:9], 0, s[20:21]
	global_load_dword v54, v[8:9], off
	v_lshl_add_u64 v[8:9], v[8:9], 0, s[20:21]
	global_load_dword v55, v[8:9], off
	v_add_u32_e32 v4, 0x2000, v146
	v_lshl_add_u64 v[12:13], v[4:5], 2, s[16:17]
	v_lshl_add_u64 v[12:13], v[12:13], 0, s[18:19]
	global_load_dword v56, v[12:13], off
	global_load_dword v57, v[12:13], off offset:2048
	s_waitcnt vmcnt(17)
	v_mul_f32_e32 v58, 0xbfb8aa3b, v40
	v_exp_f32_e32 v58, v58
	s_nop 0
	v_add_f32_e32 v58, 1.0, v58
	v_rcp_f32_e32 v58, v58
	s_nop 0
	v_mul_f32_e32 v40, v40, v58
	ds_write_b32 v1, v40 offset:0
	s_waitcnt vmcnt(16)
	v_mul_f32_e32 v59, 0xbfb8aa3b, v41
	v_exp_f32_e32 v59, v59
	s_nop 0
	v_add_f32_e32 v59, 1.0, v59
	v_rcp_f32_e32 v59, v59
	s_nop 0
	v_mul_f32_e32 v41, v41, v59
	ds_write_b32 v1, v41 offset:2048
	s_waitcnt vmcnt(15)
	v_mul_f32_e32 v58, 0xbfb8aa3b, v42
	v_exp_f32_e32 v58, v58
	s_nop 0
	v_add_f32_e32 v58, 1.0, v58
	v_rcp_f32_e32 v58, v58
	s_nop 0
	v_mul_f32_e32 v42, v42, v58
	ds_write_b32 v1, v42 offset:4096
	s_waitcnt vmcnt(14)
	v_mul_f32_e32 v59, 0xbfb8aa3b, v43
	v_exp_f32_e32 v59, v59
	s_nop 0
	v_add_f32_e32 v59, 1.0, v59
	v_rcp_f32_e32 v59, v59
	s_nop 0
	v_mul_f32_e32 v43, v43, v59
	ds_write_b32 v1, v43 offset:6144
	s_waitcnt vmcnt(13)
	v_mul_f32_e32 v58, 0xbfb8aa3b, v44
	v_exp_f32_e32 v58, v58
	s_nop 0
	v_add_f32_e32 v58, 1.0, v58
	v_rcp_f32_e32 v58, v58
	s_nop 0
	v_mul_f32_e32 v44, v44, v58
	ds_write_b32 v1, v44 offset:8192
	s_waitcnt vmcnt(12)
	v_mul_f32_e32 v59, 0xbfb8aa3b, v45
	v_exp_f32_e32 v59, v59
	s_nop 0
	v_add_f32_e32 v59, 1.0, v59
	v_rcp_f32_e32 v59, v59
	s_nop 0
	v_mul_f32_e32 v45, v45, v59
	ds_write_b32 v1, v45 offset:10240
	s_waitcnt vmcnt(11)
	v_mul_f32_e32 v58, 0xbfb8aa3b, v46
	v_exp_f32_e32 v58, v58
	s_nop 0
	v_add_f32_e32 v58, 1.0, v58
	v_rcp_f32_e32 v58, v58
	s_nop 0
	v_mul_f32_e32 v46, v46, v58
	ds_write_b32 v1, v46 offset:12288
	s_waitcnt vmcnt(10)
	v_mul_f32_e32 v59, 0xbfb8aa3b, v47
	v_exp_f32_e32 v59, v59
	s_nop 0
	v_add_f32_e32 v59, 1.0, v59
	v_rcp_f32_e32 v59, v59
	s_nop 0
	v_mul_f32_e32 v47, v47, v59
	ds_write_b32 v1, v47 offset:14336
	s_waitcnt vmcnt(9)
	v_mul_f32_e32 v58, 0xbfb8aa3b, v48
	v_exp_f32_e32 v58, v58
	s_nop 0
	v_add_f32_e32 v58, 1.0, v58
	v_rcp_f32_e32 v58, v58
	s_nop 0
	v_mul_f32_e32 v48, v48, v58
	ds_write_b32 v1, v48 offset:16384
	s_waitcnt vmcnt(8)
	v_mul_f32_e32 v59, 0xbfb8aa3b, v49
	v_exp_f32_e32 v59, v59
	s_nop 0
	v_add_f32_e32 v59, 1.0, v59
	v_rcp_f32_e32 v59, v59
	s_nop 0
	v_mul_f32_e32 v49, v49, v59
	ds_write_b32 v1, v49 offset:18432
	s_waitcnt vmcnt(7)
	v_mul_f32_e32 v58, 0xbfb8aa3b, v50
	v_exp_f32_e32 v58, v58
	s_nop 0
	v_add_f32_e32 v58, 1.0, v58
	v_rcp_f32_e32 v58, v58
	s_nop 0
	v_mul_f32_e32 v50, v50, v58
	ds_write_b32 v1, v50 offset:20480
	s_waitcnt vmcnt(6)
	v_mul_f32_e32 v59, 0xbfb8aa3b, v51
	v_exp_f32_e32 v59, v59
	s_nop 0
	v_add_f32_e32 v59, 1.0, v59
	v_rcp_f32_e32 v59, v59
	s_nop 0
	v_mul_f32_e32 v51, v51, v59
	ds_write_b32 v1, v51 offset:22528
	s_waitcnt vmcnt(5)
	v_mul_f32_e32 v58, 0xbfb8aa3b, v52
	v_exp_f32_e32 v58, v58
	s_nop 0
	v_add_f32_e32 v58, 1.0, v58
	v_rcp_f32_e32 v58, v58
	s_nop 0
	v_mul_f32_e32 v52, v52, v58
	ds_write_b32 v1, v52 offset:24576
	s_waitcnt vmcnt(4)
	v_mul_f32_e32 v59, 0xbfb8aa3b, v53
	v_exp_f32_e32 v59, v59
	s_nop 0
	v_add_f32_e32 v59, 1.0, v59
	v_rcp_f32_e32 v59, v59
	s_nop 0
	v_mul_f32_e32 v53, v53, v59
	ds_write_b32 v1, v53 offset:26624
	s_waitcnt vmcnt(3)
	v_mul_f32_e32 v58, 0xbfb8aa3b, v54
	v_exp_f32_e32 v58, v58
	s_nop 0
	v_add_f32_e32 v58, 1.0, v58
	v_rcp_f32_e32 v58, v58
	s_nop 0
	v_mul_f32_e32 v54, v54, v58
	ds_write_b32 v1, v54 offset:28672
	s_waitcnt vmcnt(2)
	v_mul_f32_e32 v59, 0xbfb8aa3b, v55
	v_exp_f32_e32 v59, v59
	s_nop 0
	v_add_f32_e32 v59, 1.0, v59
	v_rcp_f32_e32 v59, v59
	s_nop 0
	v_mul_f32_e32 v55, v55, v59
	ds_write_b32 v1, v55 offset:30720
	s_waitcnt vmcnt(1)
	v_mul_f32_e32 v58, 0xbfb8aa3b, v56
	v_exp_f32_e32 v58, v58
	s_nop 0
	v_add_f32_e32 v58, 1.0, v58
	v_rcp_f32_e32 v58, v58
	s_nop 0
	v_mul_f32_e32 v56, v56, v58
	ds_write_b32 v1, v56 offset:32768
	s_waitcnt vmcnt(0)
	v_mul_f32_e32 v59, 0xbfb8aa3b, v57
	v_exp_f32_e32 v59, v59
	s_nop 0
	v_add_f32_e32 v59, 1.0, v59
	v_rcp_f32_e32 v59, v59
	s_nop 0
	v_mul_f32_e32 v57, v57, v59
	ds_write_b32 v1, v57 offset:34816

; __device__ __forceinline__ void ph_prologue(const P& p, unsigned char* lds, int tid, int wave, int lane, int G) {
;     ...
;         const int l = task >> 7, c0 = (task & 127) * 72;
;         const bool actv = lane < 36;
;         const float* w = p.ada_w + (size_t)l * DM * 9216 + c0 + 2 * (actv ? lane : 0);
;         float acc0[9], acc1[9];
; #pragma unroll
;         for (int r = 0; r < 9; ++r) { acc0[r] = 0.f; acc1[r] = 0.f; }
;         const int kb = wave * 128;
; #pragma unroll 2
;         for (int k4 = 0; k4 < 128; k4 += 4) {
;             f32x2_ wv[4];
; #pragma unroll
;             for (int j = 0; j < 4; ++j) wv[j] = *(const f32x2_*)(w + (size_t)(kb + k4 + j) * 9216);
; #pragma unroll
;             for (int r = 0; r < 9; ++r) { const f32x4 s4 = *(const f32x4*)(sv + r * 1024 + kb + k4);
;                 acc0[r] += s4[0] * wv[0].x + s4[1] * wv[1].x + s4[2] * wv[2].x + s4[3] * wv[3].x;
;                 acc1[r] += s4[0] * wv[0].y + s4[1] * wv[1].y + s4[2] * wv[2].y + s4[3] * wv[3].y; }
;         }
.LBB0_20:
	s_and_b32 s27, s53, 0x7f
	s_ashr_i32 s26, s54, 7
	s_mul_i32 s24, s27, 0x120
	s_mul_i32 s28, s26, 0x2400000
	s_mul_hi_i32 s25, s26, 0x2400000
	s_or_b32 s24, s28, s24
	v_mov_b32_e32 v10, 0
	v_lshl_add_u64 v[8:9], v[6:7], 0, s[24:25]
	s_mov_b32 s24, -4
	s_mov_b32 s25, s33
	v_mov_b32_e32 v14, 0
	v_mov_b32_e32 v12, 0
	v_mov_b32_e32 v18, 0
	v_mov_b32_e32 v16, 0
	v_mov_b32_e32 v22, 0
	v_mov_b32_e32 v20, 0
	v_mov_b32_e32 v26, 0
	v_mov_b32_e32 v24, 0
	v_mov_b32_e32 v11, v10
	v_mov_b32_e32 v15, v10
	v_mov_b32_e32 v13, v10
	v_mov_b32_e32 v19, v10
	v_mov_b32_e32 v17, v10
	v_mov_b32_e32 v23, v10
	v_mov_b32_e32 v21, v10
	v_mov_b32_e32 v27, v10
	v_mov_b32_e32 v25, v10
	s_mov_b32 s56, s42
	s_mov_b32 s57, -1
	s_mov_b32 s58, s43
	s_mov_b32 s59, -1
	s_mov_b32 s60, s44
	s_mov_b32 s61, -1
	s_mov_b32 s62, s45
	s_mov_b32 s63, -1
	s_mov_b32 s64, s46
	s_mov_b32 s65, -1
	s_mov_b32 s66, s47
	s_mov_b32 s67, -1
	s_mov_b32 s68, s48
	s_mov_b32 s69, -1
	v_mov_b64_e32 v[218:219], v[8:9]
	s_mov_b32 s24, 0
	v_lshl_add_u64 v[204:205], v[218:219], 0, s[56:57]
	v_lshl_add_u64 v[206:207], v[218:219], 0, s[58:59]
	v_lshl_add_u64 v[208:209], v[218:219], 0, s[60:61]
	v_lshl_add_u64 v[210:211], v[218:219], 0, s[62:63]
	v_lshl_add_u64 v[212:213], v[218:219], 0, s[64:65]
	v_lshl_add_u64 v[214:215], v[218:219], 0, s[66:67]
	v_lshl_add_u64 v[216:217], v[218:219], 0, s[68:69]
	global_load_dwordx2 v[102:103], v[206:207], off
	global_load_dwordx2 v[104:105], v[214:215], off
	global_load_dwordx2 v[106:107], v[208:209], off
	global_load_dwordx2 v[108:109], v[210:211], off
	global_load_dwordx2 v[110:111], v[204:205], off
	global_load_dwordx2 v[112:113], v[216:217], off
	global_load_dwordx2 v[114:115], v[218:219], off
	global_load_dwordx2 v[116:117], v[212:213], off
	v_lshl_add_u64 v[218:219], v[218:219], 0, s[22:23]
.Lgv_loop:
	v_lshl_add_u64 v[204:205], v[218:219], 0, s[56:57]
	v_lshl_add_u64 v[206:207], v[218:219], 0, s[58:59]
	v_lshl_add_u64 v[208:209], v[218:219], 0, s[60:61]
	v_lshl_add_u64 v[210:211], v[218:219], 0, s[62:63]
	v_lshl_add_u64 v[212:213], v[218:219], 0, s[64:65]
	v_lshl_add_u64 v[214:215], v[218:219], 0, s[66:67]
	v_lshl_add_u64 v[216:217], v[218:219], 0, s[68:69]
	global_load_dwordx2 v[188:189], v[206:207], off
	global_load_dwordx2 v[190:191], v[214:215], off
	global_load_dwordx2 v[192:193], v[208:209], off
	global_load_dwordx2 v[194:195], v[210:211], off
	global_load_dwordx2 v[196:197], v[204:205], off
	global_load_dwordx2 v[198:199], v[216:217], off
	global_load_dwordx2 v[200:201], v[218:219], off
	global_load_dwordx2 v[202:203], v[212:213], off
	v_lshl_add_u64 v[218:219], v[218:219], 0, s[22:23]
	s_waitcnt vmcnt(8)
	v_mov_b32_e32 v4, s25
	s_add_i32 s25, s25, 32
	ds_read_b128 v[28:31], v4
	ds_read_b128 v[32:35], v4 offset:16
	ds_read_b128 v[38:41], v4 offset:4096
	ds_read_b128 v[42:45], v4 offset:4112
	ds_read_b128 v[46:49], v4 offset:8192
	ds_read_b128 v[50:53], v4 offset:8208
	ds_read_b128 v[54:57], v4 offset:12288
	ds_read_b128 v[58:61], v4 offset:12304
	ds_read_b128 v[62:65], v4 offset:16384
	ds_read_b128 v[66:69], v4 offset:16400
	ds_read_b128 v[70:73], v4 offset:20480
	ds_read_b128 v[74:77], v4 offset:20496
	ds_read_b128 v[78:81], v4 offset:24576
	ds_read_b128 v[82:85], v4 offset:24592
	ds_read_b128 v[86:89], v4 offset:28672
	ds_read_b128 v[90:93], v4 offset:28688
	ds_read_b128 v[94:97], v4 offset:32768
	ds_read_b128 v[98:101], v4 offset:32784
	s_waitcnt lgkmcnt(14)
	v_mov_b32_e32 v4, v31
	v_mov_b32_e32 v118, v41
	s_waitcnt lgkmcnt(13)
	v_mov_b32_e32 v120, v49
	s_waitcnt lgkmcnt(11)
	v_mov_b32_e32 v122, v57
	s_waitcnt lgkmcnt(9)
	v_mov_b32_e32 v124, v65
	s_waitcnt lgkmcnt(7)
	v_mov_b32_e32 v126, v73
	s_waitcnt lgkmcnt(5)
	v_mov_b32_e32 v128, v81
	s_waitcnt lgkmcnt(3)
	v_mov_b32_e32 v130, v89
	s_waitcnt lgkmcnt(1)
	v_mov_b32_e32 v132, v97
	v_mov_b32_e32 v134, v35
	v_mov_b32_e32 v136, v45
	v_mov_b32_e32 v138, v53
	v_mov_b32_e32 v140, v61
	v_mov_b32_e32 v142, v69
	v_mov_b32_e32 v144, v77
	v_mov_b32_e32 v148, v85
	v_mov_b32_e32 v150, v93
	s_waitcnt lgkmcnt(0)
	v_mov_b32_e32 v152, v101
	v_pk_mul_f32 v[154:155], v[102:103], v[28:29] op_sel:[0,1]
	v_pk_mul_f32 v[156:157], v[102:103], v[38:39] op_sel:[0,1]
	v_pk_mul_f32 v[158:159], v[102:103], v[46:47] op_sel:[0,1]
	v_pk_mul_f32 v[160:161], v[102:103], v[54:55] op_sel:[0,1]
	v_pk_mul_f32 v[162:163], v[102:103], v[62:63] op_sel:[0,1]
	v_pk_mul_f32 v[164:165], v[102:103], v[70:71] op_sel:[0,1]
	v_pk_mul_f32 v[166:167], v[102:103], v[78:79] op_sel:[0,1]
	v_pk_mul_f32 v[168:169], v[102:103], v[86:87] op_sel:[0,1]
	v_pk_mul_f32 v[102:103], v[102:103], v[94:95] op_sel:[0,1]
	v_pk_mul_f32 v[170:171], v[104:105], v[32:33] op_sel:[0,1]
	v_pk_mul_f32 v[172:173], v[104:105], v[42:43] op_sel:[0,1]
	v_pk_mul_f32 v[174:175], v[104:105], v[50:51] op_sel:[0,1]
	v_pk_mul_f32 v[176:177], v[104:105], v[58:59] op_sel:[0,1]
	v_pk_mul_f32 v[178:179], v[104:105], v[66:67] op_sel:[0,1]
	v_pk_mul_f32 v[180:181], v[104:105], v[74:75] op_sel:[0,1]
	v_pk_mul_f32 v[182:183], v[104:105], v[82:83] op_sel:[0,1]
	v_pk_mul_f32 v[186:187], v[104:105], v[90:91] op_sel:[0,1]
	v_pk_mul_f32 v[104:105], v[104:105], v[98:99] op_sel:[0,1]
	v_pk_fma_f32 v[28:29], v[110:111], v[28:29], v[154:155] op_sel_hi:[1,0,1]
	v_pk_fma_f32 v[38:39], v[110:111], v[38:39], v[156:157] op_sel_hi:[1,0,1]
	v_pk_fma_f32 v[46:47], v[110:111], v[46:47], v[158:159] op_sel_hi:[1,0,1]
	v_pk_fma_f32 v[54:55], v[110:111], v[54:55], v[160:161] op_sel_hi:[1,0,1]
	v_pk_fma_f32 v[62:63], v[110:111], v[62:63], v[162:163] op_sel_hi:[1,0,1]
	v_pk_fma_f32 v[70:71], v[110:111], v[70:71], v[164:165] op_sel_hi:[1,0,1]
	v_pk_fma_f32 v[78:79], v[110:111], v[78:79], v[166:167] op_sel_hi:[1,0,1]
; __device__ __forceinline__ void ph_prologue(const P& p, unsigned char* lds, int tid, int wave, int lane, int G) {
;     ...
; #pragma unroll 2
;         for (int k4 = 0; k4 < 128; k4 += 4) {
;             f32x2_ wv[4];
; #pragma unroll
;             for (int j = 0; j < 4; ++j) wv[j] = *(const f32x2_*)(w + (size_t)(kb + k4 + j) * 9216);
; #pragma unroll
;             for (int r = 0; r < 9; ++r) { const f32x4 s4 = *(const f32x4*)(sv + r * 1024 + kb + k4);
;                 acc0[r] += s4[0] * wv[0].x + s4[1] * wv[1].x + s4[2] * wv[2].x + s4[3] * wv[3].x;
;                 acc1[r] += s4[0] * wv[0].y + s4[1] * wv[1].y + s4[2] * wv[2].y + s4[3] * wv[3].y; }
;         }
	v_pk_fma_f32 v[86:87], v[110:111], v[86:87], v[168:169] op_sel_hi:[1,0,1]
	v_pk_fma_f32 v[94:95], v[110:111], v[94:95], v[102:103] op_sel_hi:[1,0,1]
	v_pk_fma_f32 v[32:33], v[116:117], v[32:33], v[170:171] op_sel_hi:[1,0,1]
	v_pk_fma_f32 v[42:43], v[116:117], v[42:43], v[172:173] op_sel_hi:[1,0,1]
	v_pk_fma_f32 v[50:51], v[116:117], v[50:51], v[174:175] op_sel_hi:[1,0,1]
	v_pk_fma_f32 v[58:59], v[116:117], v[58:59], v[176:177] op_sel_hi:[1,0,1]
	v_pk_fma_f32 v[66:67], v[116:117], v[66:67], v[178:179] op_sel_hi:[1,0,1]
	v_pk_fma_f32 v[74:75], v[116:117], v[74:75], v[180:181] op_sel_hi:[1,0,1]
	v_pk_fma_f32 v[82:83], v[116:117], v[82:83], v[182:183] op_sel_hi:[1,0,1]
	v_pk_fma_f32 v[90:91], v[116:117], v[90:91], v[186:187] op_sel_hi:[1,0,1]
	v_pk_fma_f32 v[98:99], v[116:117], v[98:99], v[104:105] op_sel_hi:[1,0,1]
	v_pk_fma_f32 v[28:29], v[106:107], v[30:31], v[28:29] op_sel_hi:[1,0,1]
	v_pk_fma_f32 v[30:31], v[106:107], v[40:41], v[38:39] op_sel_hi:[1,0,1]
	v_pk_fma_f32 v[38:39], v[106:107], v[48:49], v[46:47] op_sel_hi:[1,0,1]
	v_pk_fma_f32 v[40:41], v[106:107], v[56:57], v[54:55] op_sel_hi:[1,0,1]
	v_pk_fma_f32 v[46:47], v[106:107], v[64:65], v[62:63] op_sel_hi:[1,0,1]
	v_pk_fma_f32 v[48:49], v[106:107], v[72:73], v[70:71] op_sel_hi:[1,0,1]
	v_pk_fma_f32 v[54:55], v[106:107], v[80:81], v[78:79] op_sel_hi:[1,0,1]
	v_pk_fma_f32 v[56:57], v[106:107], v[88:89], v[86:87] op_sel_hi:[1,0,1]
	v_pk_fma_f32 v[62:63], v[106:107], v[96:97], v[94:95] op_sel_hi:[1,0,1]
	v_pk_fma_f32 v[32:33], v[112:113], v[34:35], v[32:33] op_sel_hi:[1,0,1]
	v_pk_fma_f32 v[34:35], v[112:113], v[44:45], v[42:43] op_sel_hi:[1,0,1]
	v_pk_fma_f32 v[42:43], v[112:113], v[52:53], v[50:51] op_sel_hi:[1,0,1]
	v_pk_fma_f32 v[44:45], v[112:113], v[60:61], v[58:59] op_sel_hi:[1,0,1]
	v_pk_fma_f32 v[50:51], v[112:113], v[68:69], v[66:67] op_sel_hi:[1,0,1]
	v_pk_fma_f32 v[52:53], v[112:113], v[76:77], v[74:75] op_sel_hi:[1,0,1]
	v_pk_fma_f32 v[58:59], v[112:113], v[84:85], v[82:83] op_sel_hi:[1,0,1]
	v_pk_fma_f32 v[60:61], v[112:113], v[92:93], v[90:91] op_sel_hi:[1,0,1]
	v_pk_fma_f32 v[64:65], v[112:113], v[100:101], v[98:99] op_sel_hi:[1,0,1]
	v_pk_fma_f32 v[28:29], v[108:109], v[4:5], v[28:29] op_sel_hi:[1,0,1]
	v_pk_fma_f32 v[30:31], v[108:109], v[118:119], v[30:31] op_sel_hi:[1,0,1]
	v_pk_fma_f32 v[38:39], v[108:109], v[120:121], v[38:39] op_sel_hi:[1,0,1]
	v_pk_fma_f32 v[40:41], v[108:109], v[122:123], v[40:41] op_sel_hi:[1,0,1]
	v_pk_fma_f32 v[46:47], v[108:109], v[124:125], v[46:47] op_sel_hi:[1,0,1]
	v_pk_fma_f32 v[48:49], v[108:109], v[126:127], v[48:49] op_sel_hi:[1,0,1]
	v_pk_fma_f32 v[54:55], v[108:109], v[128:129], v[54:55] op_sel_hi:[1,0,1]
	v_pk_fma_f32 v[56:57], v[108:109], v[130:131], v[56:57] op_sel_hi:[1,0,1]
	v_pk_fma_f32 v[62:63], v[108:109], v[132:133], v[62:63] op_sel_hi:[1,0,1]
	v_pk_fma_f32 v[32:33], v[114:115], v[134:135], v[32:33] op_sel_hi:[1,0,1]
	v_pk_fma_f32 v[34:35], v[114:115], v[136:137], v[34:35] op_sel_hi:[1,0,1]
	v_pk_fma_f32 v[42:43], v[114:115], v[138:139], v[42:43] op_sel_hi:[1,0,1]
	v_pk_fma_f32 v[44:45], v[114:115], v[140:141], v[44:45] op_sel_hi:[1,0,1]
	v_pk_fma_f32 v[50:51], v[114:115], v[142:143], v[50:51] op_sel_hi:[1,0,1]
	v_pk_fma_f32 v[52:53], v[114:115], v[144:145], v[52:53] op_sel_hi:[1,0,1]
	v_pk_fma_f32 v[58:59], v[114:115], v[148:149], v[58:59] op_sel_hi:[1,0,1]
	v_pk_fma_f32 v[60:61], v[114:115], v[150:151], v[60:61] op_sel_hi:[1,0,1]
	v_pk_fma_f32 v[64:65], v[114:115], v[152:153], v[64:65] op_sel_hi:[1,0,1]
	v_pk_add_f32 v[10:11], v[10:11], v[28:29]
	v_pk_add_f32 v[14:15], v[14:15], v[30:31]
	v_pk_add_f32 v[12:13], v[12:13], v[38:39]
	v_pk_add_f32 v[18:19], v[18:19], v[40:41]
	v_pk_add_f32 v[16:17], v[16:17], v[46:47]
	v_pk_add_f32 v[22:23], v[22:23], v[48:49]
	v_pk_add_f32 v[20:21], v[20:21], v[54:55]
	v_pk_add_f32 v[26:27], v[26:27], v[56:57]
	v_pk_add_f32 v[24:25], v[24:25], v[62:63]
	v_pk_add_f32 v[10:11], v[10:11], v[32:33]
	v_pk_add_f32 v[14:15], v[14:15], v[34:35]
	v_pk_add_f32 v[12:13], v[12:13], v[42:43]
	v_pk_add_f32 v[18:19], v[18:19], v[44:45]
	v_pk_add_f32 v[16:17], v[16:17], v[50:51]
	v_pk_add_f32 v[22:23], v[22:23], v[52:53]
	v_pk_add_f32 v[20:21], v[20:21], v[58:59]
	v_pk_add_f32 v[26:27], v[26:27], v[60:61]
	v_pk_add_f32 v[24:25], v[24:25], v[64:65]
	s_add_i32 s24, s24, 2
	s_cmp_lt_u32 s24, 16
	s_cbranch_scc0 .Lgv_last
; __device__ __forceinline__ void ph_prologue(const P& p, unsigned char* lds, int tid, int wave, int lane, int G) {
;     ...
; #pragma unroll 2
;         for (int k4 = 0; k4 < 128; k4 += 4) {
;             f32x2_ wv[4];
; #pragma unroll
;             for (int j = 0; j < 4; ++j) wv[j] = *(const f32x2_*)(w + (size_t)(kb + k4 + j) * 9216);
; #pragma unroll
;             for (int r = 0; r < 9; ++r) { const f32x4 s4 = *(const f32x4*)(sv + r * 1024 + kb + k4);
;                 acc0[r] += s4[0] * wv[0].x + s4[1] * wv[1].x + s4[2] * wv[2].x + s4[3] * wv[3].x;
;                 acc1[r] += s4[0] * wv[0].y + s4[1] * wv[1].y + s4[2] * wv[2].y + s4[3] * wv[3].y; }
;         }
	v_lshl_add_u64 v[204:205], v[218:219], 0, s[56:57]
	v_lshl_add_u64 v[206:207], v[218:219], 0, s[58:59]
	v_lshl_add_u64 v[208:209], v[218:219], 0, s[60:61]
	v_lshl_add_u64 v[210:211], v[218:219], 0, s[62:63]
	v_lshl_add_u64 v[212:213], v[218:219], 0, s[64:65]
	v_lshl_add_u64 v[214:215], v[218:219], 0, s[66:67]
	v_lshl_add_u64 v[216:217], v[218:219], 0, s[68:69]
	global_load_dwordx2 v[102:103], v[206:207], off
	global_load_dwordx2 v[104:105], v[214:215], off
	global_load_dwordx2 v[106:107], v[208:209], off
	global_load_dwordx2 v[108:109], v[210:211], off
	global_load_dwordx2 v[110:111], v[204:205], off
	global_load_dwordx2 v[112:113], v[216:217], off
	global_load_dwordx2 v[114:115], v[218:219], off
	global_load_dwordx2 v[116:117], v[212:213], off
	v_lshl_add_u64 v[218:219], v[218:219], 0, s[22:23]
	s_waitcnt vmcnt(8)
	v_mov_b32_e32 v4, s25
	s_add_i32 s25, s25, 32
	ds_read_b128 v[28:31], v4
	ds_read_b128 v[32:35], v4 offset:16
	ds_read_b128 v[38:41], v4 offset:4096
	ds_read_b128 v[42:45], v4 offset:4112
	ds_read_b128 v[46:49], v4 offset:8192
	ds_read_b128 v[50:53], v4 offset:8208
	ds_read_b128 v[54:57], v4 offset:12288
	ds_read_b128 v[58:61], v4 offset:12304
	ds_read_b128 v[62:65], v4 offset:16384
	ds_read_b128 v[66:69], v4 offset:16400
	ds_read_b128 v[70:73], v4 offset:20480
	ds_read_b128 v[74:77], v4 offset:20496
	ds_read_b128 v[78:81], v4 offset:24576
	ds_read_b128 v[82:85], v4 offset:24592
	ds_read_b128 v[86:89], v4 offset:28672
	ds_read_b128 v[90:93], v4 offset:28688
	ds_read_b128 v[94:97], v4 offset:32768
	ds_read_b128 v[98:101], v4 offset:32784
	s_waitcnt lgkmcnt(14)
	v_mov_b32_e32 v4, v31
	v_mov_b32_e32 v118, v41
	s_waitcnt lgkmcnt(13)
	v_mov_b32_e32 v120, v49
	s_waitcnt lgkmcnt(11)
	v_mov_b32_e32 v122, v57
	s_waitcnt lgkmcnt(9)
	v_mov_b32_e32 v124, v65
	s_waitcnt lgkmcnt(7)
	v_mov_b32_e32 v126, v73
	s_waitcnt lgkmcnt(5)
	v_mov_b32_e32 v128, v81
	s_waitcnt lgkmcnt(3)
	v_mov_b32_e32 v130, v89
	s_waitcnt lgkmcnt(1)
	v_mov_b32_e32 v132, v97
	v_mov_b32_e32 v134, v35
	v_mov_b32_e32 v136, v45
	v_mov_b32_e32 v138, v53
	v_mov_b32_e32 v140, v61
	v_mov_b32_e32 v142, v69
	v_mov_b32_e32 v144, v77
	v_mov_b32_e32 v148, v85
	v_mov_b32_e32 v150, v93
	s_waitcnt lgkmcnt(0)
	v_mov_b32_e32 v152, v101
	v_pk_mul_f32 v[154:155], v[188:189], v[28:29] op_sel:[0,1]
	v_pk_mul_f32 v[156:157], v[188:189], v[38:39] op_sel:[0,1]
	v_pk_mul_f32 v[158:159], v[188:189], v[46:47] op_sel:[0,1]
	v_pk_mul_f32 v[160:161], v[188:189], v[54:55] op_sel:[0,1]
	v_pk_mul_f32 v[162:163], v[188:189], v[62:63] op_sel:[0,1]
	v_pk_mul_f32 v[164:165], v[188:189], v[70:71] op_sel:[0,1]
	v_pk_mul_f32 v[166:167], v[188:189], v[78:79] op_sel:[0,1]
	v_pk_mul_f32 v[168:169], v[188:189], v[86:87] op_sel:[0,1]
	v_pk_mul_f32 v[188:189], v[188:189], v[94:95] op_sel:[0,1]
	v_pk_mul_f32 v[170:171], v[190:191], v[32:33] op_sel:[0,1]
	v_pk_mul_f32 v[172:173], v[190:191], v[42:43] op_sel:[0,1]
	v_pk_mul_f32 v[174:175], v[190:191], v[50:51] op_sel:[0,1]
	v_pk_mul_f32 v[176:177], v[190:191], v[58:59] op_sel:[0,1]
	v_pk_mul_f32 v[178:179], v[190:191], v[66:67] op_sel:[0,1]
	v_pk_mul_f32 v[180:181], v[190:191], v[74:75] op_sel:[0,1]
	v_pk_mul_f32 v[182:183], v[190:191], v[82:83] op_sel:[0,1]
	v_pk_mul_f32 v[186:187], v[190:191], v[90:91] op_sel:[0,1]
	v_pk_mul_f32 v[190:191], v[190:191], v[98:99] op_sel:[0,1]
	v_pk_fma_f32 v[28:29], v[196:197], v[28:29], v[154:155] op_sel_hi:[1,0,1]
	v_pk_fma_f32 v[38:39], v[196:197], v[38:39], v[156:157] op_sel_hi:[1,0,1]
	v_pk_fma_f32 v[46:47], v[196:197], v[46:47], v[158:159] op_sel_hi:[1,0,1]
	v_pk_fma_f32 v[54:55], v[196:197], v[54:55], v[160:161] op_sel_hi:[1,0,1]
	v_pk_fma_f32 v[62:63], v[196:197], v[62:63], v[162:163] op_sel_hi:[1,0,1]
	v_pk_fma_f32 v[70:71], v[196:197], v[70:71], v[164:165] op_sel_hi:[1,0,1]
	v_pk_fma_f32 v[78:79], v[196:197], v[78:79], v[166:167] op_sel_hi:[1,0,1]
	v_pk_fma_f32 v[86:87], v[196:197], v[86:87], v[168:169] op_sel_hi:[1,0,1]
	v_pk_fma_f32 v[94:95], v[196:197], v[94:95], v[188:189] op_sel_hi:[1,0,1]
	v_pk_fma_f32 v[32:33], v[202:203], v[32:33], v[170:171] op_sel_hi:[1,0,1]
	v_pk_fma_f32 v[42:43], v[202:203], v[42:43], v[172:173] op_sel_hi:[1,0,1]
	v_pk_fma_f32 v[50:51], v[202:203], v[50:51], v[174:175] op_sel_hi:[1,0,1]
	v_pk_fma_f32 v[58:59], v[202:203], v[58:59], v[176:177] op_sel_hi:[1,0,1]
	v_pk_fma_f32 v[66:67], v[202:203], v[66:67], v[178:179] op_sel_hi:[1,0,1]
	v_pk_fma_f32 v[74:75], v[202:203], v[74:75], v[180:181] op_sel_hi:[1,0,1]
	v_pk_fma_f32 v[82:83], v[202:203], v[82:83], v[182:183] op_sel_hi:[1,0,1]
	v_pk_fma_f32 v[90:91], v[202:203], v[90:91], v[186:187] op_sel_hi:[1,0,1]
	v_pk_fma_f32 v[98:99], v[202:203], v[98:99], v[190:191] op_sel_hi:[1,0,1]
	v_pk_fma_f32 v[28:29], v[192:193], v[30:31], v[28:29] op_sel_hi:[1,0,1]
	v_pk_fma_f32 v[30:31], v[192:193], v[40:41], v[38:39] op_sel_hi:[1,0,1]
	v_pk_fma_f32 v[38:39], v[192:193], v[48:49], v[46:47] op_sel_hi:[1,0,1]
	v_pk_fma_f32 v[40:41], v[192:193], v[56:57], v[54:55] op_sel_hi:[1,0,1]
	v_pk_fma_f32 v[46:47], v[192:193], v[64:65], v[62:63] op_sel_hi:[1,0,1]
	v_pk_fma_f32 v[48:49], v[192:193], v[72:73], v[70:71] op_sel_hi:[1,0,1]
	v_pk_fma_f32 v[54:55], v[192:193], v[80:81], v[78:79] op_sel_hi:[1,0,1]
	v_pk_fma_f32 v[56:57], v[192:193], v[88:89], v[86:87] op_sel_hi:[1,0,1]
	v_pk_fma_f32 v[62:63], v[192:193], v[96:97], v[94:95] op_sel_hi:[1,0,1]
	v_pk_fma_f32 v[32:33], v[198:199], v[34:35], v[32:33] op_sel_hi:[1,0,1]
	v_pk_fma_f32 v[34:35], v[198:199], v[44:45], v[42:43] op_sel_hi:[1,0,1]
	v_pk_fma_f32 v[42:43], v[198:199], v[52:53], v[50:51] op_sel_hi:[1,0,1]
	v_pk_fma_f32 v[44:45], v[198:199], v[60:61], v[58:59] op_sel_hi:[1,0,1]
; __device__ __forceinline__ void ph_prologue(const P& p, unsigned char* lds, int tid, int wave, int lane, int G) {
;     ...
; #pragma unroll 2
;         for (int k4 = 0; k4 < 128; k4 += 4) {
;             f32x2_ wv[4];
; #pragma unroll
;             for (int j = 0; j < 4; ++j) wv[j] = *(const f32x2_*)(w + (size_t)(kb + k4 + j) * 9216);
; #pragma unroll
;             for (int r = 0; r < 9; ++r) { const f32x4 s4 = *(const f32x4*)(sv + r * 1024 + kb + k4);
;                 acc0[r] += s4[0] * wv[0].x + s4[1] * wv[1].x + s4[2] * wv[2].x + s4[3] * wv[3].x;
;                 acc1[r] += s4[0] * wv[0].y + s4[1] * wv[1].y + s4[2] * wv[2].y + s4[3] * wv[3].y; }
;         }
	v_pk_fma_f32 v[50:51], v[198:199], v[68:69], v[66:67] op_sel_hi:[1,0,1]
	v_pk_fma_f32 v[52:53], v[198:199], v[76:77], v[74:75] op_sel_hi:[1,0,1]
	v_pk_fma_f32 v[58:59], v[198:199], v[84:85], v[82:83] op_sel_hi:[1,0,1]
	v_pk_fma_f32 v[60:61], v[198:199], v[92:93], v[90:91] op_sel_hi:[1,0,1]
	v_pk_fma_f32 v[64:65], v[198:199], v[100:101], v[98:99] op_sel_hi:[1,0,1]
	v_pk_fma_f32 v[28:29], v[194:195], v[4:5], v[28:29] op_sel_hi:[1,0,1]
	v_pk_fma_f32 v[30:31], v[194:195], v[118:119], v[30:31] op_sel_hi:[1,0,1]
	v_pk_fma_f32 v[38:39], v[194:195], v[120:121], v[38:39] op_sel_hi:[1,0,1]
	v_pk_fma_f32 v[40:41], v[194:195], v[122:123], v[40:41] op_sel_hi:[1,0,1]
	v_pk_fma_f32 v[46:47], v[194:195], v[124:125], v[46:47] op_sel_hi:[1,0,1]
	v_pk_fma_f32 v[48:49], v[194:195], v[126:127], v[48:49] op_sel_hi:[1,0,1]
	v_pk_fma_f32 v[54:55], v[194:195], v[128:129], v[54:55] op_sel_hi:[1,0,1]
	v_pk_fma_f32 v[56:57], v[194:195], v[130:131], v[56:57] op_sel_hi:[1,0,1]
	v_pk_fma_f32 v[62:63], v[194:195], v[132:133], v[62:63] op_sel_hi:[1,0,1]
	v_pk_fma_f32 v[32:33], v[200:201], v[134:135], v[32:33] op_sel_hi:[1,0,1]
	v_pk_fma_f32 v[34:35], v[200:201], v[136:137], v[34:35] op_sel_hi:[1,0,1]
	v_pk_fma_f32 v[42:43], v[200:201], v[138:139], v[42:43] op_sel_hi:[1,0,1]
	v_pk_fma_f32 v[44:45], v[200:201], v[140:141], v[44:45] op_sel_hi:[1,0,1]
	v_pk_fma_f32 v[50:51], v[200:201], v[142:143], v[50:51] op_sel_hi:[1,0,1]
	v_pk_fma_f32 v[52:53], v[200:201], v[144:145], v[52:53] op_sel_hi:[1,0,1]
	v_pk_fma_f32 v[58:59], v[200:201], v[148:149], v[58:59] op_sel_hi:[1,0,1]
	v_pk_fma_f32 v[60:61], v[200:201], v[150:151], v[60:61] op_sel_hi:[1,0,1]
	v_pk_fma_f32 v[64:65], v[200:201], v[152:153], v[64:65] op_sel_hi:[1,0,1]
	v_pk_add_f32 v[10:11], v[10:11], v[28:29]
	v_pk_add_f32 v[14:15], v[14:15], v[30:31]
	v_pk_add_f32 v[12:13], v[12:13], v[38:39]
	v_pk_add_f32 v[18:19], v[18:19], v[40:41]
	v_pk_add_f32 v[16:17], v[16:17], v[46:47]
	v_pk_add_f32 v[22:23], v[22:23], v[48:49]
	v_pk_add_f32 v[20:21], v[20:21], v[54:55]
	v_pk_add_f32 v[26:27], v[26:27], v[56:57]
	v_pk_add_f32 v[24:25], v[24:25], v[62:63]
	v_pk_add_f32 v[10:11], v[10:11], v[32:33]
	v_pk_add_f32 v[14:15], v[14:15], v[34:35]
	v_pk_add_f32 v[12:13], v[12:13], v[42:43]
	v_pk_add_f32 v[18:19], v[18:19], v[44:45]
	v_pk_add_f32 v[16:17], v[16:17], v[50:51]
	v_pk_add_f32 v[22:23], v[22:23], v[52:53]
	v_pk_add_f32 v[20:21], v[20:21], v[58:59]
	v_pk_add_f32 v[26:27], v[26:27], v[60:61]
	v_pk_add_f32 v[24:25], v[24:25], v[64:65]
	s_branch .Lgv_loop
.Lgv_last:
	s_waitcnt vmcnt(0)
	v_mov_b32_e32 v4, s25
	s_add_i32 s25, s25, 32
	ds_read_b128 v[28:31], v4
	ds_read_b128 v[32:35], v4 offset:16
	ds_read_b128 v[38:41], v4 offset:4096
	ds_read_b128 v[42:45], v4 offset:4112
	ds_read_b128 v[46:49], v4 offset:8192
	ds_read_b128 v[50:53], v4 offset:8208
	ds_read_b128 v[54:57], v4 offset:12288
	ds_read_b128 v[58:61], v4 offset:12304
	ds_read_b128 v[62:65], v4 offset:16384
	ds_read_b128 v[66:69], v4 offset:16400
	ds_read_b128 v[70:73], v4 offset:20480
	ds_read_b128 v[74:77], v4 offset:20496
	ds_read_b128 v[78:81], v4 offset:24576
	ds_read_b128 v[82:85], v4 offset:24592
	ds_read_b128 v[86:89], v4 offset:28672
	ds_read_b128 v[90:93], v4 offset:28688
	ds_read_b128 v[94:97], v4 offset:32768
	ds_read_b128 v[98:101], v4 offset:32784
	s_waitcnt lgkmcnt(14)
	v_mov_b32_e32 v4, v31
	v_mov_b32_e32 v118, v41
	s_waitcnt lgkmcnt(13)
	v_mov_b32_e32 v120, v49
	s_waitcnt lgkmcnt(11)
	v_mov_b32_e32 v122, v57
	s_waitcnt lgkmcnt(9)
	v_mov_b32_e32 v124, v65
	s_waitcnt lgkmcnt(7)
	v_mov_b32_e32 v126, v73
	s_waitcnt lgkmcnt(5)
	v_mov_b32_e32 v128, v81
	s_waitcnt lgkmcnt(3)
	v_mov_b32_e32 v130, v89
	s_waitcnt lgkmcnt(1)
	v_mov_b32_e32 v132, v97
	v_mov_b32_e32 v134, v35
	v_mov_b32_e32 v136, v45
	v_mov_b32_e32 v138, v53
	v_mov_b32_e32 v140, v61
	v_mov_b32_e32 v142, v69
	v_mov_b32_e32 v144, v77
	v_mov_b32_e32 v148, v85
	v_mov_b32_e32 v150, v93
	s_waitcnt lgkmcnt(0)
; __device__ __forceinline__ void ph_prologue(const P& p, unsigned char* lds, int tid, int wave, int lane, int G) {
;     ...
; #pragma unroll 2
;         for (int k4 = 0; k4 < 128; k4 += 4) {
;             f32x2_ wv[4];
; #pragma unroll
;             for (int j = 0; j < 4; ++j) wv[j] = *(const f32x2_*)(w + (size_t)(kb + k4 + j) * 9216);
; #pragma unroll
;             for (int r = 0; r < 9; ++r) { const f32x4 s4 = *(const f32x4*)(sv + r * 1024 + kb + k4);
;                 acc0[r] += s4[0] * wv[0].x + s4[1] * wv[1].x + s4[2] * wv[2].x + s4[3] * wv[3].x;
;                 acc1[r] += s4[0] * wv[0].y + s4[1] * wv[1].y + s4[2] * wv[2].y + s4[3] * wv[3].y; }
;         }
;         if (actv) {
; #pragma unroll
;             for (int r = 0; r < 9; ++r) { red[(wave * 9 + r) * 72 + 2 * lane] = acc0[r]; red[(wave * 9 + r) * 72 + 2 * lane + 1] = acc1[r]; }
;         }
	v_mov_b32_e32 v152, v101
	v_pk_mul_f32 v[154:155], v[188:189], v[28:29] op_sel:[0,1]
	v_pk_mul_f32 v[156:157], v[188:189], v[38:39] op_sel:[0,1]
	v_pk_mul_f32 v[158:159], v[188:189], v[46:47] op_sel:[0,1]
	v_pk_mul_f32 v[160:161], v[188:189], v[54:55] op_sel:[0,1]
	v_pk_mul_f32 v[162:163], v[188:189], v[62:63] op_sel:[0,1]
	v_pk_mul_f32 v[164:165], v[188:189], v[70:71] op_sel:[0,1]
	v_pk_mul_f32 v[166:167], v[188:189], v[78:79] op_sel:[0,1]
	v_pk_mul_f32 v[168:169], v[188:189], v[86:87] op_sel:[0,1]
	v_pk_mul_f32 v[188:189], v[188:189], v[94:95] op_sel:[0,1]
	v_pk_mul_f32 v[170:171], v[190:191], v[32:33] op_sel:[0,1]
	v_pk_mul_f32 v[172:173], v[190:191], v[42:43] op_sel:[0,1]
	v_pk_mul_f32 v[174:175], v[190:191], v[50:51] op_sel:[0,1]
	v_pk_mul_f32 v[176:177], v[190:191], v[58:59] op_sel:[0,1]
	v_pk_mul_f32 v[178:179], v[190:191], v[66:67] op_sel:[0,1]
	v_pk_mul_f32 v[180:181], v[190:191], v[74:75] op_sel:[0,1]
	v_pk_mul_f32 v[182:183], v[190:191], v[82:83] op_sel:[0,1]
	v_pk_mul_f32 v[186:187], v[190:191], v[90:91] op_sel:[0,1]
	v_pk_mul_f32 v[190:191], v[190:191], v[98:99] op_sel:[0,1]
	v_pk_fma_f32 v[28:29], v[196:197], v[28:29], v[154:155] op_sel_hi:[1,0,1]
	v_pk_fma_f32 v[38:39], v[196:197], v[38:39], v[156:157] op_sel_hi:[1,0,1]
	v_pk_fma_f32 v[46:47], v[196:197], v[46:47], v[158:159] op_sel_hi:[1,0,1]
	v_pk_fma_f32 v[54:55], v[196:197], v[54:55], v[160:161] op_sel_hi:[1,0,1]
	v_pk_fma_f32 v[62:63], v[196:197], v[62:63], v[162:163] op_sel_hi:[1,0,1]
	v_pk_fma_f32 v[70:71], v[196:197], v[70:71], v[164:165] op_sel_hi:[1,0,1]
	v_pk_fma_f32 v[78:79], v[196:197], v[78:79], v[166:167] op_sel_hi:[1,0,1]
	v_pk_fma_f32 v[86:87], v[196:197], v[86:87], v[168:169] op_sel_hi:[1,0,1]
	v_pk_fma_f32 v[94:95], v[196:197], v[94:95], v[188:189] op_sel_hi:[1,0,1]
	v_pk_fma_f32 v[32:33], v[202:203], v[32:33], v[170:171] op_sel_hi:[1,0,1]
	v_pk_fma_f32 v[42:43], v[202:203], v[42:43], v[172:173] op_sel_hi:[1,0,1]
	v_pk_fma_f32 v[50:51], v[202:203], v[50:51], v[174:175] op_sel_hi:[1,0,1]
	v_pk_fma_f32 v[58:59], v[202:203], v[58:59], v[176:177] op_sel_hi:[1,0,1]
	v_pk_fma_f32 v[66:67], v[202:203], v[66:67], v[178:179] op_sel_hi:[1,0,1]
	v_pk_fma_f32 v[74:75], v[202:203], v[74:75], v[180:181] op_sel_hi:[1,0,1]
	v_pk_fma_f32 v[82:83], v[202:203], v[82:83], v[182:183] op_sel_hi:[1,0,1]
	v_pk_fma_f32 v[90:91], v[202:203], v[90:91], v[186:187] op_sel_hi:[1,0,1]
	v_pk_fma_f32 v[98:99], v[202:203], v[98:99], v[190:191] op_sel_hi:[1,0,1]
	v_pk_fma_f32 v[28:29], v[192:193], v[30:31], v[28:29] op_sel_hi:[1,0,1]
	v_pk_fma_f32 v[30:31], v[192:193], v[40:41], v[38:39] op_sel_hi:[1,0,1]
	v_pk_fma_f32 v[38:39], v[192:193], v[48:49], v[46:47] op_sel_hi:[1,0,1]
	v_pk_fma_f32 v[40:41], v[192:193], v[56:57], v[54:55] op_sel_hi:[1,0,1]
	v_pk_fma_f32 v[46:47], v[192:193], v[64:65], v[62:63] op_sel_hi:[1,0,1]
	v_pk_fma_f32 v[48:49], v[192:193], v[72:73], v[70:71] op_sel_hi:[1,0,1]
	v_pk_fma_f32 v[54:55], v[192:193], v[80:81], v[78:79] op_sel_hi:[1,0,1]
	v_pk_fma_f32 v[56:57], v[192:193], v[88:89], v[86:87] op_sel_hi:[1,0,1]
	v_pk_fma_f32 v[62:63], v[192:193], v[96:97], v[94:95] op_sel_hi:[1,0,1]
	v_pk_fma_f32 v[32:33], v[198:199], v[34:35], v[32:33] op_sel_hi:[1,0,1]
	v_pk_fma_f32 v[34:35], v[198:199], v[44:45], v[42:43] op_sel_hi:[1,0,1]
	v_pk_fma_f32 v[42:43], v[198:199], v[52:53], v[50:51] op_sel_hi:[1,0,1]
	v_pk_fma_f32 v[44:45], v[198:199], v[60:61], v[58:59] op_sel_hi:[1,0,1]
	v_pk_fma_f32 v[50:51], v[198:199], v[68:69], v[66:67] op_sel_hi:[1,0,1]
	v_pk_fma_f32 v[52:53], v[198:199], v[76:77], v[74:75] op_sel_hi:[1,0,1]
	v_pk_fma_f32 v[58:59], v[198:199], v[84:85], v[82:83] op_sel_hi:[1,0,1]
	v_pk_fma_f32 v[60:61], v[198:199], v[92:93], v[90:91] op_sel_hi:[1,0,1]
	v_pk_fma_f32 v[64:65], v[198:199], v[100:101], v[98:99] op_sel_hi:[1,0,1]
	v_pk_fma_f32 v[28:29], v[194:195], v[4:5], v[28:29] op_sel_hi:[1,0,1]
	v_pk_fma_f32 v[30:31], v[194:195], v[118:119], v[30:31] op_sel_hi:[1,0,1]
	v_pk_fma_f32 v[38:39], v[194:195], v[120:121], v[38:39] op_sel_hi:[1,0,1]
	v_pk_fma_f32 v[40:41], v[194:195], v[122:123], v[40:41] op_sel_hi:[1,0,1]
	v_pk_fma_f32 v[46:47], v[194:195], v[124:125], v[46:47] op_sel_hi:[1,0,1]
	v_pk_fma_f32 v[48:49], v[194:195], v[126:127], v[48:49] op_sel_hi:[1,0,1]
	v_pk_fma_f32 v[54:55], v[194:195], v[128:129], v[54:55] op_sel_hi:[1,0,1]
	v_pk_fma_f32 v[56:57], v[194:195], v[130:131], v[56:57] op_sel_hi:[1,0,1]
	v_pk_fma_f32 v[62:63], v[194:195], v[132:133], v[62:63] op_sel_hi:[1,0,1]
	v_pk_fma_f32 v[32:33], v[200:201], v[134:135], v[32:33] op_sel_hi:[1,0,1]
	v_pk_fma_f32 v[34:35], v[200:201], v[136:137], v[34:35] op_sel_hi:[1,0,1]
	v_pk_fma_f32 v[42:43], v[200:201], v[138:139], v[42:43] op_sel_hi:[1,0,1]
	v_pk_fma_f32 v[44:45], v[200:201], v[140:141], v[44:45] op_sel_hi:[1,0,1]
	v_pk_fma_f32 v[50:51], v[200:201], v[142:143], v[50:51] op_sel_hi:[1,0,1]
	v_pk_fma_f32 v[52:53], v[200:201], v[144:145], v[52:53] op_sel_hi:[1,0,1]
	v_pk_fma_f32 v[58:59], v[200:201], v[148:149], v[58:59] op_sel_hi:[1,0,1]
	v_pk_fma_f32 v[60:61], v[200:201], v[150:151], v[60:61] op_sel_hi:[1,0,1]
	v_pk_fma_f32 v[64:65], v[200:201], v[152:153], v[64:65] op_sel_hi:[1,0,1]
	v_pk_add_f32 v[10:11], v[10:11], v[28:29]
	v_pk_add_f32 v[14:15], v[14:15], v[30:31]
	v_pk_add_f32 v[12:13], v[12:13], v[38:39]
	v_pk_add_f32 v[18:19], v[18:19], v[40:41]
	v_pk_add_f32 v[16:17], v[16:17], v[46:47]
	v_pk_add_f32 v[22:23], v[22:23], v[48:49]
	v_pk_add_f32 v[20:21], v[20:21], v[54:55]
	v_pk_add_f32 v[26:27], v[26:27], v[56:57]
	v_pk_add_f32 v[24:25], v[24:25], v[62:63]
	v_pk_add_f32 v[10:11], v[10:11], v[32:33]
	v_pk_add_f32 v[14:15], v[14:15], v[34:35]
	v_pk_add_f32 v[12:13], v[12:13], v[42:43]
	v_pk_add_f32 v[18:19], v[18:19], v[44:45]
	v_pk_add_f32 v[16:17], v[16:17], v[50:51]
	v_pk_add_f32 v[22:23], v[22:23], v[52:53]
	v_pk_add_f32 v[20:21], v[20:21], v[58:59]
	v_pk_add_f32 v[26:27], v[26:27], v[60:61]
	v_pk_add_f32 v[24:25], v[24:25], v[64:65]
	s_and_saveexec_b64 s[24:25], s[8:9]
	s_cbranch_execz .LBB0_24
	v_add_u32_e32 v4, 0x9000, v36
	ds_write2_b64 v4, v[10:11], v[14:15] offset1:36
	ds_write2_b64 v4, v[12:13], v[18:19] offset0:72 offset1:108
	ds_write2_b64 v4, v[16:17], v[22:23] offset0:144 offset1:180
	ds_write2_b64 v4, v[20:21], v[26:27] offset0:216 offset1:252
	ds_write_b64 v36, v[24:25] offset:39168

;     __host__ __device__ bool next(int i, Unit& u) const {
;         const long L = (long)i * G + c; if (L >= nwg) return false;
;         int wgid = (int)L; { const int q = nwg / NXCD, r = nwg % NXCD, xcd = wgid % NXCD, off = wgid / NXCD; wgid = (xcd < r ? xcd * (q + 1) : r * (q + 1) + (xcd - r) * q) + off; }
;         const int nig = WGM * nN, gid = wgid / nig, fm = gid * WGM, gsz = (nM - fm) < WGM ? (nM - fm) : WGM;
;         u.pm = fm + ((wgid % nig) % gsz); u.pn = (wgid % nig) / gsz; return true;
; template <class Epi, class Sched, bool ALIGN_EPI = false, bool SP2 = false>
; __device__ __forceinline__ void gemm_phase(PG8_LAS unsigned char* lds, const Gemm g, const Sched& S, const Epi& E) {
;     ...
;         const bool has_next = S.next(ui + 1, nxt);
;         const char* nA = has_next ? (const char*)g.A + (size_t)nxt.pm * tstep : cA; const char* nB = has_next ? (const char*)g.Bt + (size_t)nxt.pn * tstep : cB;
.LBB0_160:
	s_lshr_b32 s101, s101, 4
	s_add_i32 s86, s86, 1
	s_mul_i32 s6, s86, s39
	s_mul_hi_u32 s7, s86, s38
	s_add_i32 s7, s7, s6
	s_mul_i32 s6, s86, s38
	s_add_u32 s22, s6, s90
	s_addc_u32 s23, s7, s91
	s_sub_i32 s72, s22, s90
	s_sub_i32 s73, s10, s72
	s_cmp_lt_i32 s73, 1
	s_cbranch_scc1 .Lhu_done
	s_lshl_b32 s74, s73, 1
	s_cmp_gt_u32 s74, s38
	s_cbranch_scc1 .Lhu_done
	s_cmp_lt_u32 s90, s73
	s_cbranch_scc0 .Lhu_second
	s_and_b32 s101, s101, 7
	s_or_b32 s101, s101, 16
	s_branch .Lhu_done
.Lhu_second:
	s_cmp_lt_u32 s90, s74
	s_cbranch_scc0 .Lhu_done
	s_sub_u32 s22, s22, s73
	s_subb_u32 s23, s23, 0
	s_and_b32 s101, s101, 7
	s_or_b32 s101, s101, 32

; template <class Epi, class Sched, bool ALIGN_EPI = false, bool SP2 = false>
; __device__ __forceinline__ void gemm_phase(PG8_LAS unsigned char* lds, const Gemm g, const Sched& S, const Epi& E) {
;     ...
; #pragma unroll
;         for (int a = 0; a < 2; ++a)
; #pragma unroll
;             for (int b = 0; b < 2; ++b)
; #pragma unroll
;                 for (int m = 0; m < 4; ++m)
; #pragma unroll
;                     for (int n = 0; n < 2; ++n) acc[a][b][m][n] = (f32x4){0.f, 0.f, 0.f, 0.f};
;         cur = nxt; cA = nA; cB = nB; ++ui;
.LBB0_162:
	s_ashr_i32 s21, s20, 31
	s_lshl_b64 s[22:23], s[20:21], 19
	s_add_u32 s22, s46, s22
	s_addc_u32 s23, s47, s23
	s_and_b64 s[24:25], s[6:7], exec
	s_cselect_b32 s21, s23, s31
	s_cselect_b32 s27, s22, s30
	s_ashr_i32 s19, s18, 31
	s_lshl_b64 s[24:25], s[18:19], 19
	s_add_u32 s24, s48, s24
	s_addc_u32 s25, s49, s25
	s_and_b64 s[40:41], s[6:7], exec
	s_cselect_b32 s19, s25, s35
	s_cselect_b32 s50, s24, s34
	s_add_u32 s30, s30, 0x40080
	s_addc_u32 s31, s31, 0
	s_add_u32 s52, s34, 0x100
	v_mov_b32_e32 v2, 0
	s_addc_u32 s54, s35, 0
	s_mov_b32 s62, -2
	v_mov_b32_e32 v3, v2
	v_mov_b32_e32 v4, v2
	v_mov_b32_e32 v5, v2
	v_mov_b32_e32 v6, v2
	v_mov_b32_e32 v7, v2
	v_mov_b32_e32 v8, v2
	v_mov_b32_e32 v9, v2
	v_mov_b32_e32 v18, v2
	v_mov_b32_e32 v19, v2
	v_mov_b32_e32 v20, v2
	v_mov_b32_e32 v21, v2
	v_mov_b32_e32 v22, v2
	v_mov_b32_e32 v23, v2
	v_mov_b32_e32 v24, v2
	v_mov_b32_e32 v25, v2
	v_mov_b32_e32 v34, v2
	v_mov_b32_e32 v35, v2
	v_mov_b32_e32 v36, v2
	v_mov_b32_e32 v37, v2
	v_mov_b32_e32 v38, v2
	v_mov_b32_e32 v39, v2
	v_mov_b32_e32 v40, v2
	v_mov_b32_e32 v41, v2
	v_mov_b32_e32 v50, v2
	v_mov_b32_e32 v51, v2
	v_mov_b32_e32 v52, v2
	v_mov_b32_e32 v53, v2
	v_mov_b32_e32 v54, v2
	v_mov_b32_e32 v55, v2
	v_mov_b32_e32 v56, v2
	v_mov_b32_e32 v57, v2
	v_mov_b32_e32 v10, v2
	v_mov_b32_e32 v11, v2
	v_mov_b32_e32 v12, v2
	v_mov_b32_e32 v13, v2
	v_mov_b32_e32 v14, v2
	v_mov_b32_e32 v15, v2
	v_mov_b32_e32 v16, v2
	v_mov_b32_e32 v17, v2
	v_mov_b32_e32 v26, v2
	v_mov_b32_e32 v27, v2
	v_mov_b32_e32 v28, v2
	v_mov_b32_e32 v29, v2
	v_mov_b32_e32 v30, v2
	v_mov_b32_e32 v31, v2
	v_mov_b32_e32 v32, v2
	v_mov_b32_e32 v33, v2
	v_mov_b32_e32 v42, v2
	v_mov_b32_e32 v43, v2
	v_mov_b32_e32 v44, v2
	v_mov_b32_e32 v45, v2
	v_mov_b32_e32 v46, v2
	v_mov_b32_e32 v47, v2
	v_mov_b32_e32 v48, v2
	v_mov_b32_e32 v49, v2
	v_mov_b32_e32 v58, v2
	v_mov_b32_e32 v59, v2
	v_mov_b32_e32 v60, v2
	v_mov_b32_e32 v61, v2
	v_mov_b32_e32 v62, v2
	v_mov_b32_e32 v63, v2
	v_mov_b32_e32 v64, v2
	v_mov_b32_e32 v65, v2
	v_mov_b32_e32 v66, v2
	v_mov_b32_e32 v67, v2
	v_mov_b32_e32 v68, v2
	v_mov_b32_e32 v69, v2
	v_mov_b32_e32 v70, v2
	v_mov_b32_e32 v71, v2
	v_mov_b32_e32 v72, v2
	v_mov_b32_e32 v73, v2
	v_mov_b32_e32 v82, v2
	v_mov_b32_e32 v83, v2
	v_mov_b32_e32 v84, v2
	v_mov_b32_e32 v85, v2
	v_mov_b32_e32 v86, v2
	v_mov_b32_e32 v87, v2
	v_mov_b32_e32 v88, v2
	v_mov_b32_e32 v89, v2
	v_mov_b32_e32 v98, v2
	v_mov_b32_e32 v99, v2
	v_mov_b32_e32 v100, v2
	v_mov_b32_e32 v101, v2
	v_mov_b32_e32 v102, v2
	v_mov_b32_e32 v103, v2
	v_mov_b32_e32 v104, v2
	v_mov_b32_e32 v105, v2
	v_mov_b32_e32 v114, v2
	v_mov_b32_e32 v115, v2
	v_mov_b32_e32 v116, v2
	v_mov_b32_e32 v117, v2
	v_mov_b32_e32 v118, v2
	v_mov_b32_e32 v119, v2
	v_mov_b32_e32 v120, v2
	v_mov_b32_e32 v121, v2
	v_mov_b32_e32 v74, v2
	v_mov_b32_e32 v75, v2
	v_mov_b32_e32 v76, v2
	v_mov_b32_e32 v77, v2
	v_mov_b32_e32 v78, v2
	v_mov_b32_e32 v79, v2
	v_mov_b32_e32 v80, v2
	v_mov_b32_e32 v81, v2
	v_mov_b32_e32 v90, v2
	v_mov_b32_e32 v91, v2
	v_mov_b32_e32 v92, v2
	v_mov_b32_e32 v93, v2
	v_mov_b32_e32 v94, v2
	v_mov_b32_e32 v95, v2
	v_mov_b32_e32 v96, v2
	v_mov_b32_e32 v97, v2
	v_mov_b32_e32 v106, v2
	v_mov_b32_e32 v107, v2
	v_mov_b32_e32 v108, v2
	v_mov_b32_e32 v109, v2
	v_mov_b32_e32 v110, v2
	v_mov_b32_e32 v111, v2
	v_mov_b32_e32 v112, v2
	v_mov_b32_e32 v113, v2
	v_mov_b32_e32 v122, v2
	v_mov_b32_e32 v123, v2
	v_mov_b32_e32 v124, v2
	v_mov_b32_e32 v125, v2
	v_mov_b32_e32 v126, v2
	v_mov_b32_e32 v127, v2
	v_mov_b32_e32 v128, v2
	v_mov_b32_e32 v129, v2
	s_and_b32 s98, s101, 7
	s_cmp_lg_u32 s98, 0
	s_cbranch_scc0 .LBB0_163
	s_and_b32 s98, s101, 7
	s_cmp_eq_u32 s98, 1
	s_cbranch_scc1 .Lku_a0
	s_branch .Lku_a1

; __device__ __forceinline__ unsigned pk2(float lo, float hi) { unsigned r; asm("v_cvt_pk_bf16_f32 %0, %1, %2" : "=v"(r) : "v"(lo), "v"(hi)); return r; }
; __device__ __forceinline__ float siluf(float v) { return v * __builtin_amdgcn_rcpf(1.f + __expf(-v)); }
;     __device__ __forceinline__ void operator()(const f32x4 (&acc)[2][2][4][2], const Unit& u, int wr, int wc, int fr, int fq) const {
; #pragma unroll
;         for (int ai = 0; ai < 2; ++ai)
; #pragma unroll
;             for (int m = 0; m < 4; ++m) {
;                 const int row = u.pm * 256 + ai * 128 + wr * 64 + m * 16 + fr;
;                 const f32x4 g0 = acc[ai][0][m][0], u0 = acc[ai][0][m][1], g1 = acc[ai][1][m][0], u1 = acc[ai][1][m][1];
;                 u32x4 w;
;                 w.x = pk2(siluf(g0[0]) * u0[0], siluf(g0[1]) * u0[1]); w.y = pk2(siluf(g0[2]) * u0[2], siluf(g0[3]) * u0[3]);
;                 w.z = pk2(siluf(g1[0]) * u1[0], siluf(g1[1]) * u1[1]); w.w = pk2(siluf(g1[2]) * u1[2], siluf(g1[3]) * u1[3]);
;                 *(u32x4*)(act + (size_t)row * DFF + u.pn * 128 + wc * 32 + 8 * fq) = w;
;             }
.LBB0_166:
	s_and_b32 s98, s101, 7
	s_cmp_eq_u32 s98, 2
	s_cbranch_scc1 .Lku_epi_skip0
	v_mul_f32_e32 v156, 0xbfb8aa3b, v126
	v_exp_f32_e32 v156, v156
	s_lshl_b32 s19, s28, 8
	s_lshl_b32 s26, s26, 7
	v_add_u32_e32 v155, s19, v143
	v_add_f32_e32 v156, 1.0, v156
	v_rcp_f32_e32 v156, v156
	s_movk_i32 s21, 0x1600
	s_ashr_i32 s27, s26, 31
	s_lshl_b64 s[26:27], s[26:27], 1
	v_mul_f32_e32 v126, v126, v156
	v_mul_f32_e32 v122, v122, v126
	v_mul_f32_e32 v126, 0xbfb8aa3b, v127
	v_exp_f32_e32 v126, v126
	s_andn2_b64 vcc, exec, s[6:7]
	v_add_f32_e32 v126, 1.0, v126
	v_rcp_f32_e32 v126, v126
	s_nop 0
	v_mul_f32_e32 v126, v127, v126
	v_mul_f32_e32 v123, v123, v126
	v_cvt_pk_bf16_f32 v122, v122, v123
	v_mul_f32_e32 v123, 0xbfb8aa3b, v128
	v_exp_f32_e32 v123, v123
	s_nop 0
	v_add_f32_e32 v123, 1.0, v123
	v_rcp_f32_e32 v123, v123
	s_nop 0
	v_mul_f32_e32 v123, v128, v123
	v_mul_f32_e32 v123, v124, v123
	v_mul_f32_e32 v124, 0xbfb8aa3b, v129
	v_exp_f32_e32 v124, v124
	s_nop 0
	v_add_f32_e32 v124, 1.0, v124
	v_rcp_f32_e32 v124, v124
	s_nop 0
	v_mul_f32_e32 v124, v129, v124
	v_mul_f32_e32 v124, v125, v124
	v_cvt_pk_bf16_f32 v123, v123, v124
	v_mul_f32_e32 v124, 0xbfb8aa3b, v118
	v_exp_f32_e32 v124, v124
	s_nop 0
	v_add_f32_e32 v124, 1.0, v124
	v_rcp_f32_e32 v124, v124
	s_nop 0
	v_mul_f32_e32 v118, v118, v124
	v_mul_f32_e32 v114, v114, v118
	v_mul_f32_e32 v118, 0xbfb8aa3b, v119
	v_exp_f32_e32 v118, v118
	s_nop 0
	v_add_f32_e32 v118, 1.0, v118
	v_rcp_f32_e32 v118, v118
	s_nop 0
	v_mul_f32_e32 v118, v119, v118
	v_mul_f32_e32 v115, v115, v118
	v_cvt_pk_bf16_f32 v124, v114, v115
	v_mul_f32_e32 v114, 0xbfb8aa3b, v120
	v_mul_f32_e32 v115, 0xbfb8aa3b, v121
	v_exp_f32_e32 v114, v114
	v_exp_f32_e32 v115, v115
	v_add_f32_e32 v114, 1.0, v114
	v_add_f32_e32 v115, 1.0, v115
	v_rcp_f32_e32 v114, v114
	v_rcp_f32_e32 v115, v115
	v_mul_f32_e32 v114, v120, v114
	v_mul_f32_e32 v115, v121, v115
	v_mul_f32_e32 v114, v116, v114
	v_mul_f32_e32 v115, v117, v115
	v_cvt_pk_bf16_f32 v125, v114, v115
	v_mov_b64_e32 v[114:115], s[14:15]
	v_mad_i64_i32 v[116:117], s[30:31], v155, s21, v[114:115]
	v_lshl_add_u64 v[116:117], v[116:117], 0, s[26:27]
	v_lshl_add_u64 v[116:117], v[116:117], 0, s[64:65]
	v_lshl_add_u64 v[116:117], v[116:117], 0, v[0:1]
	global_store_dwordx4 v[116:117], v[122:125], off
	v_mul_f32_e32 v117, 0xbfb8aa3b, v110
	v_exp_f32_e32 v117, v117
	v_add_u32_e32 v116, s19, v147
	v_add_f32_e32 v117, 1.0, v117
	v_rcp_f32_e32 v117, v117
	s_nop 0
	v_mul_f32_e32 v110, v110, v117
	v_mul_f32_e32 v106, v106, v110
	v_mul_f32_e32 v110, 0xbfb8aa3b, v111
	v_exp_f32_e32 v110, v110
	s_nop 0
	v_add_f32_e32 v110, 1.0, v110
	v_rcp_f32_e32 v110, v110
	s_nop 0
	v_mul_f32_e32 v110, v111, v110
	v_mul_f32_e32 v107, v107, v110
	v_cvt_pk_bf16_f32 v106, v106, v107
	v_mul_f32_e32 v107, 0xbfb8aa3b, v112
	v_exp_f32_e32 v107, v107
	s_nop 0
	v_add_f32_e32 v107, 1.0, v107
	v_rcp_f32_e32 v107, v107
	s_nop 0
	v_mul_f32_e32 v107, v112, v107
	v_mul_f32_e32 v107, v108, v107
	v_mul_f32_e32 v108, 0xbfb8aa3b, v113
	v_exp_f32_e32 v108, v108
	s_nop 0
	v_add_f32_e32 v108, 1.0, v108
	v_rcp_f32_e32 v108, v108
	s_nop 0
	v_mul_f32_e32 v108, v113, v108
	v_mul_f32_e32 v108, v109, v108
	v_cvt_pk_bf16_f32 v107, v107, v108
	v_mul_f32_e32 v108, 0xbfb8aa3b, v102
	v_exp_f32_e32 v108, v108
	s_nop 0
	v_add_f32_e32 v108, 1.0, v108
	v_rcp_f32_e32 v108, v108
	s_nop 0
	v_mul_f32_e32 v102, v102, v108
	v_mul_f32_e32 v98, v98, v102
	v_mul_f32_e32 v102, 0xbfb8aa3b, v103
	v_exp_f32_e32 v102, v102
	s_nop 0
	v_add_f32_e32 v102, 1.0, v102
	v_rcp_f32_e32 v102, v102
	s_nop 0
	v_mul_f32_e32 v102, v103, v102
	v_mul_f32_e32 v99, v99, v102
	v_cvt_pk_bf16_f32 v108, v98, v99
	v_mul_f32_e32 v98, 0xbfb8aa3b, v104
	v_mul_f32_e32 v99, 0xbfb8aa3b, v105
	v_exp_f32_e32 v98, v98
	v_exp_f32_e32 v99, v99
	v_add_f32_e32 v98, 1.0, v98
	v_add_f32_e32 v99, 1.0, v99
	v_rcp_f32_e32 v98, v98
	v_rcp_f32_e32 v99, v99
	v_mul_f32_e32 v98, v104, v98
	v_mul_f32_e32 v99, v105, v99
	v_mul_f32_e32 v98, v100, v98
	v_mul_f32_e32 v99, v101, v99
	v_cvt_pk_bf16_f32 v109, v98, v99
	v_mad_i64_i32 v[98:99], s[30:31], v116, s21, v[114:115]
; __device__ __forceinline__ unsigned pk2(float lo, float hi) { unsigned r; asm("v_cvt_pk_bf16_f32 %0, %1, %2" : "=v"(r) : "v"(lo), "v"(hi)); return r; }
; __device__ __forceinline__ float siluf(float v) { return v * __builtin_amdgcn_rcpf(1.f + __expf(-v)); }
;     __device__ __forceinline__ void operator()(const f32x4 (&acc)[2][2][4][2], const Unit& u, int wr, int wc, int fr, int fq) const {
; #pragma unroll
;         for (int ai = 0; ai < 2; ++ai)
; #pragma unroll
;             for (int m = 0; m < 4; ++m) {
;                 const int row = u.pm * 256 + ai * 128 + wr * 64 + m * 16 + fr;
;                 const f32x4 g0 = acc[ai][0][m][0], u0 = acc[ai][0][m][1], g1 = acc[ai][1][m][0], u1 = acc[ai][1][m][1];
;                 u32x4 w;
;                 w.x = pk2(siluf(g0[0]) * u0[0], siluf(g0[1]) * u0[1]); w.y = pk2(siluf(g0[2]) * u0[2], siluf(g0[3]) * u0[3]);
;                 w.z = pk2(siluf(g1[0]) * u1[0], siluf(g1[1]) * u1[1]); w.w = pk2(siluf(g1[2]) * u1[2], siluf(g1[3]) * u1[3]);
;                 *(u32x4*)(act + (size_t)row * DFF + u.pn * 128 + wc * 32 + 8 * fq) = w;
;             }
	v_lshl_add_u64 v[98:99], v[98:99], 0, s[26:27]
	v_lshl_add_u64 v[98:99], v[98:99], 0, s[64:65]
	v_lshl_add_u64 v[98:99], v[98:99], 0, v[0:1]
	global_store_dwordx4 v[98:99], v[106:109], off
	v_mul_f32_e32 v99, 0xbfb8aa3b, v94
	v_exp_f32_e32 v99, v99
	v_add_u32_e32 v98, s19, v148
	v_add_f32_e32 v99, 1.0, v99
	v_rcp_f32_e32 v99, v99
	s_nop 0
	v_mul_f32_e32 v94, v94, v99
	v_mul_f32_e32 v90, v90, v94
	v_mul_f32_e32 v94, 0xbfb8aa3b, v95
	v_exp_f32_e32 v94, v94
	s_nop 0
	v_add_f32_e32 v94, 1.0, v94
	v_rcp_f32_e32 v94, v94
	s_nop 0
	v_mul_f32_e32 v94, v95, v94
	v_mul_f32_e32 v91, v91, v94
	v_cvt_pk_bf16_f32 v90, v90, v91
	v_mul_f32_e32 v91, 0xbfb8aa3b, v96
	v_exp_f32_e32 v91, v91
	s_nop 0
	v_add_f32_e32 v91, 1.0, v91
	v_rcp_f32_e32 v91, v91
	s_nop 0
	v_mul_f32_e32 v91, v96, v91
	v_mul_f32_e32 v91, v92, v91
	v_mul_f32_e32 v92, 0xbfb8aa3b, v97
	v_exp_f32_e32 v92, v92
	s_nop 0
	v_add_f32_e32 v92, 1.0, v92
	v_rcp_f32_e32 v92, v92
	s_nop 0
	v_mul_f32_e32 v92, v97, v92
	v_mul_f32_e32 v92, v93, v92
	v_cvt_pk_bf16_f32 v91, v91, v92
	v_mul_f32_e32 v92, 0xbfb8aa3b, v86
	v_exp_f32_e32 v92, v92
	s_nop 0
	v_add_f32_e32 v92, 1.0, v92
	v_rcp_f32_e32 v92, v92
	s_nop 0
	v_mul_f32_e32 v86, v86, v92
	v_mul_f32_e32 v82, v82, v86
	v_mul_f32_e32 v86, 0xbfb8aa3b, v87
	v_exp_f32_e32 v86, v86
	s_nop 0
	v_add_f32_e32 v86, 1.0, v86
	v_rcp_f32_e32 v86, v86
	s_nop 0
	v_mul_f32_e32 v86, v87, v86
	v_mul_f32_e32 v83, v83, v86
	v_cvt_pk_bf16_f32 v92, v82, v83
	v_mul_f32_e32 v82, 0xbfb8aa3b, v88
	v_mul_f32_e32 v83, 0xbfb8aa3b, v89
	v_exp_f32_e32 v82, v82
	v_exp_f32_e32 v83, v83
	v_add_f32_e32 v82, 1.0, v82
	v_add_f32_e32 v83, 1.0, v83
	v_rcp_f32_e32 v82, v82
	v_rcp_f32_e32 v83, v83
	v_mul_f32_e32 v82, v88, v82
	v_mul_f32_e32 v83, v89, v83
	v_mul_f32_e32 v82, v84, v82
	v_mul_f32_e32 v83, v85, v83
	v_cvt_pk_bf16_f32 v93, v82, v83
	v_mad_i64_i32 v[82:83], s[30:31], v98, s21, v[114:115]
	v_lshl_add_u64 v[82:83], v[82:83], 0, s[26:27]
	v_lshl_add_u64 v[82:83], v[82:83], 0, s[64:65]
	v_lshl_add_u64 v[82:83], v[82:83], 0, v[0:1]
	global_store_dwordx4 v[82:83], v[90:93], off
	v_mul_f32_e32 v83, 0xbfb8aa3b, v78
	v_exp_f32_e32 v83, v83
	v_add_u32_e32 v82, s19, v149
	v_add_f32_e32 v83, 1.0, v83
	v_rcp_f32_e32 v83, v83
	s_nop 0
	v_mul_f32_e32 v78, v78, v83
	v_mul_f32_e32 v74, v74, v78
	v_mul_f32_e32 v78, 0xbfb8aa3b, v79
	v_exp_f32_e32 v78, v78
	s_nop 0
	v_add_f32_e32 v78, 1.0, v78
	v_rcp_f32_e32 v78, v78
	s_nop 0
	v_mul_f32_e32 v78, v79, v78
	v_mul_f32_e32 v75, v75, v78
	v_cvt_pk_bf16_f32 v74, v74, v75
	v_mul_f32_e32 v75, 0xbfb8aa3b, v80
	v_exp_f32_e32 v75, v75
	s_nop 0
	v_add_f32_e32 v75, 1.0, v75
	v_rcp_f32_e32 v75, v75
	s_nop 0
	v_mul_f32_e32 v75, v80, v75
	v_mul_f32_e32 v75, v76, v75
	v_mul_f32_e32 v76, 0xbfb8aa3b, v81
	v_exp_f32_e32 v76, v76
	s_nop 0
	v_add_f32_e32 v76, 1.0, v76
	v_rcp_f32_e32 v76, v76
	s_nop 0
	v_mul_f32_e32 v76, v81, v76
	v_mul_f32_e32 v76, v77, v76
	v_cvt_pk_bf16_f32 v75, v75, v76
	v_mul_f32_e32 v76, 0xbfb8aa3b, v70
	v_exp_f32_e32 v76, v76
	s_nop 0
	v_add_f32_e32 v76, 1.0, v76
	v_rcp_f32_e32 v76, v76
	s_nop 0
	v_mul_f32_e32 v70, v70, v76
	v_mul_f32_e32 v66, v66, v70
	v_mul_f32_e32 v70, 0xbfb8aa3b, v71
	v_exp_f32_e32 v70, v70
	s_nop 0
	v_add_f32_e32 v70, 1.0, v70
	v_rcp_f32_e32 v70, v70
	s_nop 0
	v_mul_f32_e32 v70, v71, v70
	v_mul_f32_e32 v67, v67, v70
	v_cvt_pk_bf16_f32 v76, v66, v67
	v_mul_f32_e32 v66, 0xbfb8aa3b, v72
	v_mul_f32_e32 v67, 0xbfb8aa3b, v73
	v_exp_f32_e32 v66, v66
	v_exp_f32_e32 v67, v67
	v_add_f32_e32 v66, 1.0, v66
	v_add_f32_e32 v67, 1.0, v67
	v_rcp_f32_e32 v66, v66
	v_rcp_f32_e32 v67, v67
	v_mul_f32_e32 v66, v72, v66
	v_mul_f32_e32 v67, v73, v67
	v_mul_f32_e32 v66, v68, v66
	v_mul_f32_e32 v67, v69, v67
	v_cvt_pk_bf16_f32 v77, v66, v67
	v_mad_i64_i32 v[66:67], s[30:31], v82, s21, v[114:115]
	v_lshl_add_u64 v[66:67], v[66:67], 0, s[26:27]
	v_lshl_add_u64 v[66:67], v[66:67], 0, s[64:65]
	v_lshl_add_u64 v[66:67], v[66:67], 0, v[0:1]
	global_store_dwordx4 v[66:67], v[74:77], off
	s_and_b32 s98, s101, 7
	s_cmp_eq_u32 s98, 1
	s_cbranch_scc1 .Lku_epi_skip1
	s_branch .Lku_epi_g4

;     __host__ __device__ bool next(int i, Unit& u) const {
;         const long L = (long)i * G + c; if (L >= nwg) return false;
;         int wgid = (int)L; { const int q = nwg / NXCD, r = nwg % NXCD, xcd = wgid % NXCD, off = wgid / NXCD; wgid = (xcd < r ? xcd * (q + 1) : r * (q + 1) + (xcd - r) * q) + off; }
;         const int nig = WGM * nN, gid = wgid / nig, fm = gid * WGM, gsz = (nM - fm) < WGM ? (nM - fm) : WGM;
;         u.pm = fm + ((wgid % nig) % gsz); u.pn = (wgid % nig) / gsz; return true;
.LBB0_842:
	s_lshr_b32 s101, s101, 4
	s_add_i32 s11, s11, 1
	s_mul_i32 s6, s11, s39
	s_mul_hi_u32 s7, s11, s38
	s_add_i32 s7, s7, s6
	s_mul_i32 s6, s11, s38
	v_readlane_b32 s8, v254, 56
	v_readlane_b32 s9, v254, 57
	s_add_u32 s6, s6, s8
	s_addc_u32 s7, s7, s9
	s_sub_i32 s80, s6, s8
	s_sub_i32 s81, s64, s80
	s_cmp_lt_i32 s81, 1
	s_cbranch_scc1 .Lhq_done
	s_lshl_b32 s82, s81, 2
	s_cmp_gt_u32 s82, s38
	s_cbranch_scc1 .Lhq_done
	s_cmp_ge_u32 s8, s82
	s_cbranch_scc1 .Lhq_done
	s_and_b32 s101, s101, 7
	s_or_b32 s101, s101, 16
	s_mov_b32 s80, s8
	s_cmp_lt_u32 s80, s81
	s_cbranch_scc1 .Lhq_done
	s_sub_u32 s80, s80, s81
	s_and_b32 s101, s101, 7
	s_or_b32 s101, s101, 32
	s_cmp_lt_u32 s80, s81
	s_cbranch_scc1 .Lhq_adj
	s_sub_u32 s80, s80, s81
	s_and_b32 s101, s101, 7
	s_or_b32 s101, s101, 48
	s_cmp_lt_u32 s80, s81
	s_cbranch_scc1 .Lhq_adj
	s_sub_u32 s80, s80, s81
	s_and_b32 s101, s101, 7
	s_or_b32 s101, s101, 64

; template <class Epi, class Sched, bool ALIGN_EPI = false, bool SP2 = false>
; __device__ __forceinline__ void gemm_phase(PG8_LAS unsigned char* lds, const Gemm g, const Sched& S, const Epi& E) {
;     ...
; #pragma unroll
;         for (int a = 0; a < 2; ++a)
; #pragma unroll
;             for (int b = 0; b < 2; ++b)
; #pragma unroll
;                 for (int m = 0; m < 4; ++m)
; #pragma unroll
;                     for (int n = 0; n < 2; ++n) acc[a][b][m][n] = (f32x4){0.f, 0.f, 0.f, 0.f};
;         cur = nxt; cA = nA; cB = nB; ++ui;
.LBB0_848:
	s_add_u32 s48, s48, 0x80
	s_addc_u32 s49, s49, 0
	s_add_u32 s80, s76, 0x100
	v_mov_b32_e32 v2, 0
	s_addc_u32 s81, s77, 0
	s_mov_b32 s76, 0
	v_mov_b32_e32 v3, v2
	v_mov_b32_e32 v4, v2
	v_mov_b32_e32 v5, v2
	v_mov_b32_e32 v6, v2
	v_mov_b32_e32 v7, v2
	v_mov_b32_e32 v8, v2
	v_mov_b32_e32 v9, v2
	v_mov_b32_e32 v18, v2
	v_mov_b32_e32 v19, v2
	v_mov_b32_e32 v20, v2
	v_mov_b32_e32 v21, v2
	v_mov_b32_e32 v22, v2
	v_mov_b32_e32 v23, v2
	v_mov_b32_e32 v24, v2
	v_mov_b32_e32 v25, v2
	v_mov_b32_e32 v34, v2
	v_mov_b32_e32 v35, v2
	v_mov_b32_e32 v36, v2
	v_mov_b32_e32 v37, v2
	v_mov_b32_e32 v38, v2
	v_mov_b32_e32 v39, v2
	v_mov_b32_e32 v40, v2
	v_mov_b32_e32 v41, v2
	v_mov_b32_e32 v50, v2
	v_mov_b32_e32 v51, v2
	v_mov_b32_e32 v52, v2
	v_mov_b32_e32 v53, v2
	v_mov_b32_e32 v54, v2
	v_mov_b32_e32 v55, v2
	v_mov_b32_e32 v56, v2
	v_mov_b32_e32 v57, v2
	v_mov_b32_e32 v10, v2
	v_mov_b32_e32 v11, v2
	v_mov_b32_e32 v12, v2
	v_mov_b32_e32 v13, v2
	v_mov_b32_e32 v14, v2
	v_mov_b32_e32 v15, v2
	v_mov_b32_e32 v16, v2
	v_mov_b32_e32 v17, v2
	v_mov_b32_e32 v26, v2
	v_mov_b32_e32 v27, v2
	v_mov_b32_e32 v28, v2
	v_mov_b32_e32 v29, v2
	v_mov_b32_e32 v30, v2
	v_mov_b32_e32 v31, v2
	v_mov_b32_e32 v32, v2
	v_mov_b32_e32 v33, v2
	v_mov_b32_e32 v42, v2
	v_mov_b32_e32 v43, v2
	v_mov_b32_e32 v44, v2
	v_mov_b32_e32 v45, v2
	v_mov_b32_e32 v46, v2
	v_mov_b32_e32 v47, v2
	v_mov_b32_e32 v48, v2
	v_mov_b32_e32 v49, v2
	v_mov_b32_e32 v58, v2
	v_mov_b32_e32 v59, v2
	v_mov_b32_e32 v60, v2
	v_mov_b32_e32 v61, v2
	v_mov_b32_e32 v62, v2
	v_mov_b32_e32 v63, v2
	v_mov_b32_e32 v64, v2
	v_mov_b32_e32 v65, v2
	v_mov_b32_e32 v66, v2
	v_mov_b32_e32 v67, v2
	v_mov_b32_e32 v68, v2
	v_mov_b32_e32 v69, v2
	v_mov_b32_e32 v70, v2
	v_mov_b32_e32 v71, v2
	v_mov_b32_e32 v72, v2
	v_mov_b32_e32 v73, v2
	v_mov_b32_e32 v82, v2
	v_mov_b32_e32 v83, v2
	v_mov_b32_e32 v84, v2
	v_mov_b32_e32 v85, v2
	v_mov_b32_e32 v86, v2
	v_mov_b32_e32 v87, v2
	v_mov_b32_e32 v88, v2
	v_mov_b32_e32 v89, v2
	v_mov_b32_e32 v98, v2
	v_mov_b32_e32 v99, v2
	v_mov_b32_e32 v100, v2
	v_mov_b32_e32 v101, v2
	v_mov_b32_e32 v102, v2
	v_mov_b32_e32 v103, v2
	v_mov_b32_e32 v104, v2
	v_mov_b32_e32 v105, v2
	v_mov_b32_e32 v114, v2
	v_mov_b32_e32 v115, v2
	v_mov_b32_e32 v116, v2
	v_mov_b32_e32 v117, v2
	v_mov_b32_e32 v118, v2
	v_mov_b32_e32 v119, v2
	v_mov_b32_e32 v120, v2
	v_mov_b32_e32 v121, v2
	v_mov_b32_e32 v74, v2
	v_mov_b32_e32 v75, v2
	v_mov_b32_e32 v76, v2
	v_mov_b32_e32 v77, v2
	v_mov_b32_e32 v78, v2
	v_mov_b32_e32 v79, v2
	v_mov_b32_e32 v80, v2
	v_mov_b32_e32 v81, v2
	v_mov_b32_e32 v90, v2
	v_mov_b32_e32 v91, v2
	v_mov_b32_e32 v92, v2
	v_mov_b32_e32 v93, v2
	v_mov_b32_e32 v94, v2
	v_mov_b32_e32 v95, v2
	v_mov_b32_e32 v96, v2
	v_mov_b32_e32 v97, v2
	v_mov_b32_e32 v106, v2
	v_mov_b32_e32 v107, v2
	v_mov_b32_e32 v108, v2
	v_mov_b32_e32 v109, v2
	v_mov_b32_e32 v110, v2
	v_mov_b32_e32 v111, v2
	v_mov_b32_e32 v112, v2
	v_mov_b32_e32 v113, v2
	v_mov_b32_e32 v122, v2
	v_mov_b32_e32 v123, v2
	v_mov_b32_e32 v124, v2
	v_mov_b32_e32 v125, v2
	v_mov_b32_e32 v126, v2
	v_mov_b32_e32 v127, v2
	v_mov_b32_e32 v128, v2
	v_mov_b32_e32 v129, v2
	s_and_b32 s98, s101, 7
	s_cmp_lg_u32 s98, 0
	s_cbranch_scc0 .LBB0_849
	s_and_b32 s98, s101, 7
	s_cmp_eq_u32 s98, 1
	s_cbranch_scc1 .Lkq_1
	s_and_b32 s98, s101, 7
	s_cmp_eq_u32 s98, 2
	s_cbranch_scc1 .Lkq_2
	s_and_b32 s98, s101, 7
	s_cmp_eq_u32 s98, 3
	s_cbranch_scc1 .Lkq_3
	s_branch .Lkq_4

;     __device__ __forceinline__ void operator()(const f32x4 (&acc)[2][2][4][2], const Unit& u, int wr, int wc, int fr, int fq) const {
;         const bool lat = u.pm < 64; const int mr = lat ? (u.pm >> 3) : 8;
;         const float* sp = lat ? srclat : srcctx; float* dp = lat ? dstlat : dstctx;
;         const int col0 = u.pn * 256 + wc * 32 + 8 * fq;
;         const size_t off0 = (size_t)((lat ? u.pm : u.pm - 64) * 256 + wr * 64 + fr) * DM + col0;
;         sp += off0; dp += off0;
;         const float* gp = gate + (size_t)mr * 9216 + col0;
;         f32x4 gv[2][2];
; #pragma unroll
;         for (int bj = 0; bj < 2; ++bj)
; #pragma unroll
;             for (int n = 0; n < 2; ++n) gv[bj][n] = *(const f32x4*)(gp + bj * 128 + n * 4) * scale;
.LBB0_854:
	s_lshl_b32 s52, s52, 8
	s_add_i32 s59, s52, 0xffffc000
	s_and_b64 s[82:83], s[82:83], exec
	s_cselect_b32 s52, s52, s59
	s_lshl_b64 s[76:77], s[76:77], 2
	v_lshl_or_b32 v136, s62, 8, v164
	s_add_u32 s76, s75, s76
	v_ashrrev_i32_e32 v137, 31, v136
	s_addc_u32 s77, s78, s77
	v_lshl_add_u64 v[170:171], v[136:137], 2, s[76:77]
	global_load_dwordx4 v[148:151], v[170:171], off offset:16
	global_load_dwordx4 v[152:155], v[170:171], off
	v_add_u32_e32 v144, s52, v143
	v_ashrrev_i32_e32 v145, 31, v144
	v_lshlrev_b64 v[144:145], 10, v[144:145]
	v_lshl_add_u64 v[144:145], v[144:145], 0, v[136:137]
	v_lshlrev_b64 v[162:163], 2, v[144:145]
	v_lshl_add_u64 v[156:157], s[80:81], 0, v[162:163]
	v_lshl_add_u64 v[162:163], s[48:49], 0, v[162:163]
	s_mov_b64 s[48:49], 0x10000
	s_mov_b32 s52, 0x10000
	s_mov_b32 s0, 0x30000
	s_mov_b32 s61, 0xb0000
	s_waitcnt vmcnt(0)
	v_pk_mul_f32 v[136:137], s[42:43], v[150:151]
	v_pk_mul_f32 v[144:145], s[2:3], v[148:149]
	global_load_dwordx4 v[166:169], v[170:171], off offset:528
	global_load_dwordx4 v[148:151], v[170:171], off offset:512
	v_pk_mul_f32 v[158:159], s[42:43], v[154:155]
	v_pk_mul_f32 v[160:161], s[2:3], v[152:153]
	s_waitcnt vmcnt(0)
	v_pk_mul_f32 v[152:153], s[42:43], v[150:151]
	v_pk_mul_f32 v[154:155], s[2:3], v[148:149]
	v_pk_mul_f32 v[148:149], s[42:43], v[168:169]
	v_pk_mul_f32 v[150:151], s[2:3], v[166:167]
	s_and_b32 s98, s101, 7
	s_cmp_lg_u32 s98, 0
	s_cbranch_scc0 .Lkq_epi_full
	s_and_b32 s98, s101, 7
	s_cmp_eq_u32 s98, 1
	s_cbranch_scc1 .Lkq_epiQ1
	s_and_b32 s98, s101, 7
	s_cmp_eq_u32 s98, 2
	s_cbranch_scc1 .Lkq_epiQ2
	s_and_b32 s98, s101, 7
	s_cmp_eq_u32 s98, 3
	s_cbranch_scc1 .Lkq_epiQ3
	s_branch .Lkq_epiQ4

;     __device__ __forceinline__ void operator()(const f32x4 (&acc)[2][2][4][2], const Unit& u, int wr, int wc, int fr, int fq) const {
;     ...
; #pragma unroll
;         for (int ai = 0; ai < 2; ++ai)
; #pragma unroll
;             for (int m = 0; m < 4; ++m) {
;                 const int ro = (ai * 128 + m * 16) * DM;
;                 f32x4 s[2][2];
; #pragma unroll
;                 for (int bj = 0; bj < 2; ++bj)
; #pragma unroll
;                     for (int n = 0; n < 2; ++n) s[bj][n] = *(const f32x4*)(sp + ro + bj * 128 + n * 4);
; #pragma unroll
;                 for (int bj = 0; bj < 2; ++bj)
; #pragma unroll
;                     for (int n = 0; n < 2; ++n) *(f32x4*)(dp + ro + bj * 128 + n * 4) = s[bj][n] + gv[bj][n] * acc[ai][bj][m][n];
;                 asm volatile("" ::: "memory");
;             }
.Lkq_epiQ1:
	s_mov_b64 s[48:49], 0x0
	v_lshl_add_u64 v[54:55], v[156:157], 0, s[48:49]
	v_lshl_add_u64 v[50:51], v[162:163], 0, s[48:49]
	s_mov_b64 s[48:49], 0x10000
	v_lshl_add_u64 v[38:39], v[156:157], 0, s[48:49]
	v_lshl_add_u64 v[34:35], v[162:163], 0, s[48:49]
	s_mov_b64 s[48:49], 0x20000
	v_lshl_add_u64 v[22:23], v[156:157], 0, s[48:49]
	v_lshl_add_u64 v[18:19], v[162:163], 0, s[48:49]
	s_mov_b64 s[48:49], 0x30000
	v_lshl_add_u64 v[6:7], v[156:157], 0, s[48:49]
	v_lshl_add_u64 v[2:3], v[162:163], 0, s[48:49]
	global_load_dwordx4 v[62:65], v[54:55], off
	global_load_dwordx4 v[58:61], v[54:55], off offset:16
	global_load_dwordx4 v[46:49], v[38:39], off
	global_load_dwordx4 v[42:45], v[38:39], off offset:16
	global_load_dwordx4 v[30:33], v[22:23], off
	global_load_dwordx4 v[26:29], v[22:23], off offset:16
	global_load_dwordx4 v[14:17], v[6:7], off
	global_load_dwordx4 v[10:13], v[6:7], off offset:16
	s_waitcnt vmcnt(6)
	v_pk_fma_f32 v[126:127], v[126:127], v[160:161], v[62:63]
	v_pk_fma_f32 v[128:129], v[128:129], v[158:159], v[64:65]
	v_pk_fma_f32 v[122:123], v[122:123], v[144:145], v[58:59]
	v_pk_fma_f32 v[124:125], v[124:125], v[136:137], v[60:61]
	global_store_dwordx4 v[50:51], v[126:129], off
	global_store_dwordx4 v[50:51], v[122:125], off offset:16
	s_waitcnt vmcnt(6)
	v_pk_fma_f32 v[110:111], v[110:111], v[160:161], v[46:47]
	v_pk_fma_f32 v[112:113], v[112:113], v[158:159], v[48:49]
	v_pk_fma_f32 v[106:107], v[106:107], v[144:145], v[42:43]
	v_pk_fma_f32 v[108:109], v[108:109], v[136:137], v[44:45]
	global_store_dwordx4 v[34:35], v[110:113], off
	global_store_dwordx4 v[34:35], v[106:109], off offset:16
	s_waitcnt vmcnt(6)
	v_pk_fma_f32 v[94:95], v[94:95], v[160:161], v[30:31]
	v_pk_fma_f32 v[96:97], v[96:97], v[158:159], v[32:33]
	v_pk_fma_f32 v[90:91], v[90:91], v[144:145], v[26:27]
	v_pk_fma_f32 v[92:93], v[92:93], v[136:137], v[28:29]
	global_store_dwordx4 v[18:19], v[94:97], off
	global_store_dwordx4 v[18:19], v[90:93], off offset:16
	s_waitcnt vmcnt(6)
	v_pk_fma_f32 v[78:79], v[78:79], v[160:161], v[14:15]
	v_pk_fma_f32 v[80:81], v[80:81], v[158:159], v[16:17]
	v_pk_fma_f32 v[74:75], v[74:75], v[144:145], v[10:11]
	v_pk_fma_f32 v[76:77], v[76:77], v[136:137], v[12:13]
	global_store_dwordx4 v[2:3], v[78:81], off
	global_store_dwordx4 v[2:3], v[74:77], off offset:16
	s_mov_b64 s[48:49], -1
	s_branch .Lkq_epi_end
.Lkq_epiQ2:
	s_mov_b64 s[48:49], 0x80000
	v_lshl_add_u64 v[118:119], v[156:157], 0, s[48:49]
	v_lshl_add_u64 v[114:115], v[162:163], 0, s[48:49]
	s_mov_b64 s[48:49], 0x90000
	v_lshl_add_u64 v[102:103], v[156:157], 0, s[48:49]
	v_lshl_add_u64 v[98:99], v[162:163], 0, s[48:49]
	s_mov_b64 s[48:49], 0xa0000
	v_lshl_add_u64 v[86:87], v[156:157], 0, s[48:49]
	v_lshl_add_u64 v[82:83], v[162:163], 0, s[48:49]
	s_mov_b64 s[48:49], 0xb0000
	v_lshl_add_u64 v[70:71], v[156:157], 0, s[48:49]
	v_lshl_add_u64 v[66:67], v[162:163], 0, s[48:49]
	global_load_dwordx4 v[126:129], v[118:119], off
	global_load_dwordx4 v[122:125], v[118:119], off offset:16
	global_load_dwordx4 v[110:113], v[102:103], off
	global_load_dwordx4 v[106:109], v[102:103], off offset:16
	global_load_dwordx4 v[94:97], v[86:87], off
	global_load_dwordx4 v[90:93], v[86:87], off offset:16
	global_load_dwordx4 v[78:81], v[70:71], off
	global_load_dwordx4 v[74:77], v[70:71], off offset:16
	s_waitcnt vmcnt(6)
	v_pk_fma_f32 v[62:63], v[62:63], v[160:161], v[126:127]
	v_pk_fma_f32 v[64:65], v[64:65], v[158:159], v[128:129]
	v_pk_fma_f32 v[58:59], v[58:59], v[144:145], v[122:123]
	v_pk_fma_f32 v[60:61], v[60:61], v[136:137], v[124:125]
	global_store_dwordx4 v[114:115], v[62:65], off
	global_store_dwordx4 v[114:115], v[58:61], off offset:16
	s_waitcnt vmcnt(6)
	v_pk_fma_f32 v[46:47], v[46:47], v[160:161], v[110:111]
	v_pk_fma_f32 v[48:49], v[48:49], v[158:159], v[112:113]
	v_pk_fma_f32 v[42:43], v[42:43], v[144:145], v[106:107]
	v_pk_fma_f32 v[44:45], v[44:45], v[136:137], v[108:109]
	global_store_dwordx4 v[98:99], v[46:49], off
	global_store_dwordx4 v[98:99], v[42:45], off offset:16
	s_waitcnt vmcnt(6)
	v_pk_fma_f32 v[30:31], v[30:31], v[160:161], v[94:95]
	v_pk_fma_f32 v[32:33], v[32:33], v[158:159], v[96:97]
	v_pk_fma_f32 v[26:27], v[26:27], v[144:145], v[90:91]
	v_pk_fma_f32 v[28:29], v[28:29], v[136:137], v[92:93]
	global_store_dwordx4 v[82:83], v[30:33], off
	global_store_dwordx4 v[82:83], v[26:29], off offset:16
	s_waitcnt vmcnt(6)
	v_pk_fma_f32 v[14:15], v[14:15], v[160:161], v[78:79]
	v_pk_fma_f32 v[16:17], v[16:17], v[158:159], v[80:81]
	v_pk_fma_f32 v[10:11], v[10:11], v[144:145], v[74:75]
	v_pk_fma_f32 v[12:13], v[12:13], v[136:137], v[76:77]
	global_store_dwordx4 v[66:67], v[14:17], off
	global_store_dwordx4 v[66:67], v[10:13], off offset:16
	s_mov_b64 s[48:49], -1
	s_branch .Lkq_epi_end
;     __device__ __forceinline__ void operator()(const f32x4 (&acc)[2][2][4][2], const Unit& u, int wr, int wc, int fr, int fq) const {
;     ...
; #pragma unroll
;         for (int ai = 0; ai < 2; ++ai)
; #pragma unroll
;             for (int m = 0; m < 4; ++m) {
;                 const int ro = (ai * 128 + m * 16) * DM;
;                 f32x4 s[2][2];
; #pragma unroll
;                 for (int bj = 0; bj < 2; ++bj)
; #pragma unroll
;                     for (int n = 0; n < 2; ++n) s[bj][n] = *(const f32x4*)(sp + ro + bj * 128 + n * 4);
; #pragma unroll
;                 for (int bj = 0; bj < 2; ++bj)
; #pragma unroll
;                     for (int n = 0; n < 2; ++n) *(f32x4*)(dp + ro + bj * 128 + n * 4) = s[bj][n] + gv[bj][n] * acc[ai][bj][m][n];
;                 asm volatile("" ::: "memory");
;             }
.Lkq_epiQ3:
	s_mov_b64 s[48:49], 0x200
	v_lshl_add_u64 v[54:55], v[156:157], 0, s[48:49]
	v_lshl_add_u64 v[50:51], v[162:163], 0, s[48:49]
	s_mov_b64 s[48:49], 0x10200
	v_lshl_add_u64 v[38:39], v[156:157], 0, s[48:49]
	v_lshl_add_u64 v[34:35], v[162:163], 0, s[48:49]
	s_mov_b64 s[48:49], 0x20200
	v_lshl_add_u64 v[22:23], v[156:157], 0, s[48:49]
	v_lshl_add_u64 v[18:19], v[162:163], 0, s[48:49]
	s_mov_b64 s[48:49], 0x30200
	v_lshl_add_u64 v[6:7], v[156:157], 0, s[48:49]
	v_lshl_add_u64 v[2:3], v[162:163], 0, s[48:49]
	global_load_dwordx4 v[62:65], v[54:55], off
	global_load_dwordx4 v[58:61], v[54:55], off offset:16
	global_load_dwordx4 v[46:49], v[38:39], off
	global_load_dwordx4 v[42:45], v[38:39], off offset:16
	global_load_dwordx4 v[30:33], v[22:23], off
	global_load_dwordx4 v[26:29], v[22:23], off offset:16
	global_load_dwordx4 v[14:17], v[6:7], off
	global_load_dwordx4 v[10:13], v[6:7], off offset:16
	s_waitcnt vmcnt(6)
	v_pk_fma_f32 v[118:119], v[118:119], v[154:155], v[62:63]
	v_pk_fma_f32 v[120:121], v[120:121], v[152:153], v[64:65]
	v_pk_fma_f32 v[114:115], v[114:115], v[150:151], v[58:59]
	v_pk_fma_f32 v[116:117], v[116:117], v[148:149], v[60:61]
	global_store_dwordx4 v[50:51], v[118:121], off
	global_store_dwordx4 v[50:51], v[114:117], off offset:16
	s_waitcnt vmcnt(6)
	v_pk_fma_f32 v[102:103], v[102:103], v[154:155], v[46:47]
	v_pk_fma_f32 v[104:105], v[104:105], v[152:153], v[48:49]
	v_pk_fma_f32 v[98:99], v[98:99], v[150:151], v[42:43]
	v_pk_fma_f32 v[100:101], v[100:101], v[148:149], v[44:45]
	global_store_dwordx4 v[34:35], v[102:105], off
	global_store_dwordx4 v[34:35], v[98:101], off offset:16
	s_waitcnt vmcnt(6)
	v_pk_fma_f32 v[86:87], v[86:87], v[154:155], v[30:31]
	v_pk_fma_f32 v[88:89], v[88:89], v[152:153], v[32:33]
	v_pk_fma_f32 v[82:83], v[82:83], v[150:151], v[26:27]
	v_pk_fma_f32 v[84:85], v[84:85], v[148:149], v[28:29]
	global_store_dwordx4 v[18:19], v[86:89], off
	global_store_dwordx4 v[18:19], v[82:85], off offset:16
	s_waitcnt vmcnt(6)
	v_pk_fma_f32 v[70:71], v[70:71], v[154:155], v[14:15]
	v_pk_fma_f32 v[72:73], v[72:73], v[152:153], v[16:17]
	v_pk_fma_f32 v[66:67], v[66:67], v[150:151], v[10:11]
	v_pk_fma_f32 v[68:69], v[68:69], v[148:149], v[12:13]
	global_store_dwordx4 v[2:3], v[70:73], off
	global_store_dwordx4 v[2:3], v[66:69], off offset:16
	s_mov_b64 s[48:49], -1
	s_branch .Lkq_epi_end
.Lkq_epiQ4:
	s_mov_b64 s[48:49], 0x80200
	v_lshl_add_u64 v[118:119], v[156:157], 0, s[48:49]
	v_lshl_add_u64 v[114:115], v[162:163], 0, s[48:49]
	s_mov_b64 s[48:49], 0x90200
	v_lshl_add_u64 v[102:103], v[156:157], 0, s[48:49]
	v_lshl_add_u64 v[98:99], v[162:163], 0, s[48:49]
	s_mov_b64 s[48:49], 0xa0200
	v_lshl_add_u64 v[86:87], v[156:157], 0, s[48:49]
	v_lshl_add_u64 v[82:83], v[162:163], 0, s[48:49]
	s_mov_b64 s[48:49], 0xb0200
	v_lshl_add_u64 v[70:71], v[156:157], 0, s[48:49]
	v_lshl_add_u64 v[66:67], v[162:163], 0, s[48:49]
	global_load_dwordx4 v[126:129], v[118:119], off
	global_load_dwordx4 v[122:125], v[118:119], off offset:16
	global_load_dwordx4 v[110:113], v[102:103], off
	global_load_dwordx4 v[106:109], v[102:103], off offset:16
	global_load_dwordx4 v[94:97], v[86:87], off
	global_load_dwordx4 v[90:93], v[86:87], off offset:16
	global_load_dwordx4 v[78:81], v[70:71], off
	global_load_dwordx4 v[74:77], v[70:71], off offset:16
	s_waitcnt vmcnt(6)
	v_pk_fma_f32 v[54:55], v[54:55], v[154:155], v[126:127]
	v_pk_fma_f32 v[56:57], v[56:57], v[152:153], v[128:129]
	v_pk_fma_f32 v[50:51], v[50:51], v[150:151], v[122:123]
	v_pk_fma_f32 v[52:53], v[52:53], v[148:149], v[124:125]
	global_store_dwordx4 v[114:115], v[54:57], off
	global_store_dwordx4 v[114:115], v[50:53], off offset:16
	s_waitcnt vmcnt(6)
	v_pk_fma_f32 v[38:39], v[38:39], v[154:155], v[110:111]
	v_pk_fma_f32 v[40:41], v[40:41], v[152:153], v[112:113]
	v_pk_fma_f32 v[34:35], v[34:35], v[150:151], v[106:107]
	v_pk_fma_f32 v[36:37], v[36:37], v[148:149], v[108:109]
	global_store_dwordx4 v[98:99], v[38:41], off
	global_store_dwordx4 v[98:99], v[34:37], off offset:16
	s_waitcnt vmcnt(6)
	v_pk_fma_f32 v[22:23], v[22:23], v[154:155], v[94:95]
	v_pk_fma_f32 v[24:25], v[24:25], v[152:153], v[96:97]
	v_pk_fma_f32 v[18:19], v[18:19], v[150:151], v[90:91]
	v_pk_fma_f32 v[20:21], v[20:21], v[148:149], v[92:93]
	global_store_dwordx4 v[82:83], v[22:25], off
	global_store_dwordx4 v[82:83], v[18:21], off offset:16
	s_waitcnt vmcnt(6)
	v_pk_fma_f32 v[6:7], v[6:7], v[154:155], v[78:79]
	v_pk_fma_f32 v[8:9], v[8:9], v[152:153], v[80:81]
	v_pk_fma_f32 v[2:3], v[2:3], v[150:151], v[74:75]
	v_pk_fma_f32 v[4:5], v[4:5], v[148:149], v[76:77]
	global_store_dwordx4 v[66:67], v[6:9], off
	global_store_dwordx4 v[66:67], v[2:5], off offset:16
	s_mov_b64 s[48:49], -1
	s_branch .Lkq_epi_end
